# v11 + nt (streaming) policy on the ret_scan and attention loads
# speedup vs baseline: 1.0015x; 1.0015x over previous
; #define LAS __attribute__((address_space(3)))
; #define ATT_RANGE(r0, lo, hi) do { int ss_, se_; if ((r0) < TP) { ss_ = (r0) & ~8191; se_ = ss_ + 8192; } else { ss_ = TP + (((r0) - TP) & ~2047); se_ = ss_ + 2048; } \
;         lo = ((r0) - 128 < ss_) ? ((ss_ - ((r0) - 128)) >> 6) : 0; hi = ((r0) + 128 >= se_) ? (((se_ - 64) - ((r0) - 128)) >> 6) : 4; } while (0)
; #define ATT_ISSUE(r0, kb) do { const bf16_t* src_ = proj + (size_t)((r0) - 128 + 64 * (kb) + skey) * DIN + 512 + sdch * 8; \
;         pk[0] = *(const u32x4*)src_; pv[0] = *(const u32x4*)(src_ + 128); pk[1] = *(const u32x4*)(src_ + 64); pv[1] = *(const u32x4*)(src_ + 192); } while (0)
; __device__ __forceinline__ void attn_phase(const Params& p, LAS unsigned char* lds, int G) {
;     const int tid = threadIdx.x, lane = tid & 63, wave = tid >> 6, fr = lane & 15, fq = lane >> 4;
;     const bf16_t* proj = (const bf16_t*)(p.ws + WS_HID); bf16_t* mix = (bf16_t*)(p.ws + WS_ACTB);
;     LAS bf16_t* Kl = (LAS bf16_t*)lds;
;     LAS bf16_t* Vl = (LAS bf16_t*)(lds + 18432);
;     LAS bf16_t* Pl = (LAS bf16_t*)(lds + 36864 + wave * 9216);
;     LAS float* stat = (LAS float*)(lds + 110592);
;     const int h = wave, kvh = h >> 2;
;     const float sink = p.in[8][h];
;     const int skey = tid >> 3, sdch = tid & 7;
;     const int trb = (8 * fq + (fr >> 2)) * 72 + 4 * (fr & 3);
;     u32x4 pk[2], pv[2];
;     ...
;     int unit = blockIdx.x;
;     if (unit < T / 64) { int lo, hi; ATT_RANGE(unit * 64, lo, hi); ATT_ISSUE(unit * 64, lo); (void)hi; }
.LBB0_535:
	s_load_dwordx2 s[2:3], s[88:89], 0xa0
	s_waitcnt lgkmcnt(0)
	s_cmp_lt_i32 s2, 5
	s_cselect_b64 s[2:3], -1, 0
	s_and_b64 s[4:5], s[2:3], s[0:1]
	s_andn2_b64 vcc, exec, s[4:5]
	s_cbranch_vccnz .LBB0_579
	s_load_dwordx2 s[0:1], s[88:89], 0x40
	v_lshrrev_b32_e32 v3, 6, v198
	v_lshlrev_b32_e32 v0, 2, v3
	s_add_u32 s2, s92, 0xf000000
	s_addc_u32 s3, s93, 0
	s_waitcnt lgkmcnt(0)
	global_load_dword v202, v0, s[0:1]
	v_and_b32_e32 v0, 7, v198
	s_cmpk_lt_i32 s90, 0x300
	v_lshrrev_b32_e32 v203, 3, v198
	s_cselect_b64 s[0:1], -1, 0
	s_cmpk_gt_i32 s90, 0x2ff
	v_lshlrev_b32_e32 v0, 4, v0
	s_cbranch_scc1 .LBB0_538
	s_lshl_b32 s6, s90, 6
	s_cmpk_lt_i32 s90, 0x200
	s_movk_i32 s7, 0xe000
	s_cselect_b32 s7, s7, 0x7ffff800
	s_and_b32 s7, s7, s6
	s_addk_i32 s6, 0xff80
	s_max_i32 s6, s6, s7
	v_add_u32_e32 v1, s6, v203
	s_movk_i32 s6, 0x1600
	v_mov_b64_e32 v[4:5], s[2:3]
	v_mad_i64_i32 v[4:5], s[6:7], v1, s6, v[4:5]
	v_mov_b32_e32 v1, 0
	v_lshl_add_u64 v[4:5], v[4:5], 0, v[0:1]
	global_load_dwordx4 v[16:19], v[4:5], off offset:1024 nt
	global_load_dwordx4 v[28:31], v[4:5], off offset:1152 nt
	global_load_dwordx4 v[20:23], v[4:5], off offset:1280 nt
	global_load_dwordx4 v[24:27], v[4:5], off offset:1408 nt

; #define LAS __attribute__((address_space(3)))
; #define ATT_RANGE(r0, lo, hi) do { int ss_, se_; if ((r0) < TP) { ss_ = (r0) & ~8191; se_ = ss_ + 8192; } else { ss_ = TP + (((r0) - TP) & ~2047); se_ = ss_ + 2048; } \
;         lo = ((r0) - 128 < ss_) ? ((ss_ - ((r0) - 128)) >> 6) : 0; hi = ((r0) + 128 >= se_) ? (((se_ - 64) - ((r0) - 128)) >> 6) : 4; } while (0)
; #define ATT_ISSUE(r0, kb) do { const bf16_t* src_ = proj + (size_t)((r0) - 128 + 64 * (kb) + skey) * DIN + 512 + sdch * 8; \
;         pk[0] = *(const u32x4*)src_; pv[0] = *(const u32x4*)(src_ + 128); pk[1] = *(const u32x4*)(src_ + 64); pv[1] = *(const u32x4*)(src_ + 192); } while (0)
; __device__ __forceinline__ void attn_phase(const Params& p, LAS unsigned char* lds, int G) {
;     ...
;     for (; unit < T / 64; unit += G) {
;         const int row0 = unit * 64; int kb_lo, kb_hi; ATT_RANGE(row0, kb_lo, kb_hi);
;         bf16x8 qf[4][2];
; #pragma unroll
;         for (int m = 0; m < 4; ++m)
; #pragma unroll
;             for (int k = 0; k < 2; ++k) qf[m][k] = *(const bf16x8*)(proj + (size_t)(row0 + 16 * m + fr) * DIN + h * 64 + 32 * k + 8 * fq);
;         f32x4 o[4][4]; float mrow[4], lrow[4];
; #pragma unroll
;         for (int m = 0; m < 4; ++m) { mrow[m] = sink; lrow[m] = 1.f;
; #pragma unroll
;             for (int n = 0; n < 4; ++n) o[m][n] = (f32x4){0.f, 0.f, 0.f, 0.f}; }
;         for (int kb = kb_lo; kb <= kb_hi; ++kb) {
;             const int kstart = row0 - 128 + 64 * kb;
;             __syncthreads();
; #pragma unroll
;             for (int i = 0; i < 2; ++i) {
;                 *(LAS u32x4*)(Kl + (i * 64 + skey) * 72 + sdch * 8) = pk[i]; *(LAS u32x4*)(Vl + (i * 64 + skey) * 72 + sdch * 8) = pv[i];
;             }
;             __syncthreads();
;             if (kb < kb_hi) { ATT_ISSUE(row0, kb + 1); }
;             else if (unit + G < T / 64) { int lo2, hi2; ATT_RANGE((unit + G) * 64, lo2, hi2); ATT_ISSUE((unit + G) * 64, lo2); (void)hi2; }
.LBB0_541:
	s_lshl_b32 s2, s18, 6
	s_and_b32 s3, s2, 0xffffe000
	s_and_b32 s9, s2, 0x7ffff800
	s_add_i32 s8, s3, 0x2000
	s_add_i32 s10, s9, 0x800
	s_cmpk_lt_i32 s18, 0x200
	s_cselect_b32 s8, s8, s10
	s_cselect_b32 s3, s3, s9
	s_add_i32 s9, s2, 0xffffff80
	s_sub_i32 s12, s8, s2
	s_sub_i32 s10, s3, s9
	s_add_i32 s12, s12, 64
	s_lshr_b32 s10, s10, 6
	s_add_i32 s11, s2, 0x80
	s_ashr_i32 s12, s12, 6
	s_cmp_gt_i32 s3, s9
	v_or_b32_e32 v188, s2, v199
	s_cselect_b32 s19, s10, 0
	s_cmp_ge_i32 s11, s8
	v_or_b32_e32 v186, 16, v188
	v_or_b32_e32 v184, 32, v188
	v_or_b32_e32 v182, 48, v188
	s_cselect_b32 s20, s12, 4
	v_ashrrev_i32_e32 v189, 31, v188
	v_ashrrev_i32_e32 v187, 31, v186
	v_ashrrev_i32_e32 v185, 31, v184
	v_ashrrev_i32_e32 v183, 31, v182
	s_cmp_le_i32 s19, s20
	s_mov_b64 s[2:3], -1
	s_cbranch_scc0 .LBB0_564
	v_mad_i64_i32 v[0:1], s[2:3], v188, s15, v[176:177]
	global_load_dwordx4 v[96:99], v[0:1], off nt
	global_load_dwordx4 v[100:103], v[0:1], off offset:64 nt
	v_mad_i64_i32 v[0:1], s[2:3], v186, s15, v[176:177]
	global_load_dwordx4 v[104:107], v[0:1], off nt
	global_load_dwordx4 v[108:111], v[0:1], off offset:64 nt
	v_mad_i64_i32 v[0:1], s[2:3], v184, s15, v[176:177]
	global_load_dwordx4 v[112:115], v[0:1], off nt
	global_load_dwordx4 v[116:119], v[0:1], off offset:64 nt
	v_mad_i64_i32 v[0:1], s[2:3], v182, s15, v[176:177]
	global_load_dwordx4 v[120:123], v[0:1], off nt
	global_load_dwordx4 v[124:127], v[0:1], off offset:64 nt
	s_add_i32 s2, s18, s86
	s_cmpk_lt_i32 s2, 0x300
	s_cselect_b64 s[8:9], -1, 0
	s_lshl_b32 s3, s2, 6
	s_cmpk_lt_i32 s2, 0x200
	s_cselect_b32 s2, 0xffffe000, s14
	s_and_b32 s2, s2, s3
	s_addk_i32 s3, 0xff80
	s_max_i32 s2, s3, s2
	v_add_u32_e32 v0, s2, v203
	v_mad_i64_i32 v[190:191], s[2:3], v0, s15, v[180:181]
	v_and_b32_e32 v0, 64, v217
	v_xor_b32_e32 v221, 16, v217
	v_add_u32_e32 v219, 64, v0
	v_cmp_lt_i32_e32 vcc, v221, v219
	v_xor_b32_e32 v220, 32, v217
	s_lshl_b32 s21, s19, 6
	v_cndmask_b32_e32 v0, v217, v221, vcc
	v_cmp_lt_i32_e32 vcc, v220, v219
	v_lshlrev_b32_e32 v222, 2, v0
	v_mov_b32_e32 v36, 0
	v_cndmask_b32_e32 v0, v217, v220, vcc
	v_lshlrev_b32_e32 v223, 2, v0
	s_waitcnt vmcnt(0)
	v_mov_b64_e32 v[8:9], v[20:21]
	v_mov_b64_e32 v[12:13], v[24:25]
	v_mov_b64_e32 v[0:1], v[16:17]
	v_mov_b64_e32 v[4:5], v[28:29]
	v_subrev_u32_e32 v236, s21, v211
	v_mov_b32_e32 v226, 1.0
	v_mov_b32_e32 v224, v212
	v_mov_b32_e32 v225, v210
	v_mov_b32_e32 v231, v202
	v_mov_b32_e32 v235, v202
	v_mov_b32_e32 v233, v202
	v_mov_b32_e32 v232, v202
	v_mov_b32_e32 v229, 1.0
	v_mov_b32_e32 v228, 1.0
	v_mov_b32_e32 v227, 1.0
	v_mov_b64_e32 v[10:11], v[22:23]
	v_mov_b64_e32 v[14:15], v[26:27]
	v_mov_b64_e32 v[2:3], v[18:19]
	v_mov_b64_e32 v[6:7], v[30:31]
	v_mov_b32_e32 v37, v36
	v_mov_b32_e32 v38, v36
	v_mov_b32_e32 v39, v36
	v_mov_b32_e32 v60, v36
	v_mov_b32_e32 v61, v36
	v_mov_b32_e32 v62, v36
	v_mov_b32_e32 v63, v36
	v_mov_b32_e32 v52, v36
	v_mov_b32_e32 v53, v36
	v_mov_b32_e32 v54, v36
	v_mov_b32_e32 v55, v36
	v_mov_b32_e32 v56, v36
	v_mov_b32_e32 v57, v36
	v_mov_b32_e32 v58, v36
	v_mov_b32_e32 v59, v36
	v_mov_b32_e32 v72, v36
	v_mov_b32_e32 v73, v36
	v_mov_b32_e32 v74, v36
	v_mov_b32_e32 v75, v36
	v_mov_b32_e32 v64, v36
	v_mov_b32_e32 v65, v36
	v_mov_b32_e32 v66, v36
	v_mov_b32_e32 v67, v36
	v_mov_b32_e32 v68, v36
	v_mov_b32_e32 v69, v36
	v_mov_b32_e32 v70, v36
	v_mov_b32_e32 v71, v36
	v_mov_b32_e32 v76, v36
	v_mov_b32_e32 v77, v36
	v_mov_b32_e32 v78, v36
	v_mov_b32_e32 v79, v36
	v_mov_b32_e32 v92, v36
	v_mov_b32_e32 v93, v36
	v_mov_b32_e32 v94, v36
	v_mov_b32_e32 v95, v36
	v_mov_b32_e32 v80, v36
	v_mov_b32_e32 v81, v36
	v_mov_b32_e32 v82, v36
	v_mov_b32_e32 v83, v36
	v_mov_b32_e32 v88, v36
	v_mov_b32_e32 v89, v36
	v_mov_b32_e32 v90, v36
	v_mov_b32_e32 v91, v36
	v_mov_b32_e32 v84, v36
	v_mov_b32_e32 v85, v36
	v_mov_b32_e32 v86, v36
	v_mov_b32_e32 v87, v36
	v_mov_b32_e32 v48, v36
	v_mov_b32_e32 v49, v36
	v_mov_b32_e32 v50, v36
	v_mov_b32_e32 v51, v36
	v_mov_b32_e32 v32, v36
	v_mov_b32_e32 v33, v36
	v_mov_b32_e32 v34, v36
	v_mov_b32_e32 v35, v36
	v_mov_b32_e32 v44, v36
	v_mov_b32_e32 v45, v36
	v_mov_b32_e32 v46, v36
	v_mov_b32_e32 v47, v36
	v_mov_b32_e32 v40, v36
	v_mov_b32_e32 v41, v36
	v_mov_b32_e32 v42, v36
	v_mov_b32_e32 v43, v36
.LBB0_543:
	s_cmp_ge_i32 s19, s20
	s_cselect_b64 s[10:11], -1, 0
	s_mov_b64 s[2:3], -1
	s_and_b64 vcc, exec, s[10:11]
	s_barrier
	s_waitcnt vmcnt(3)
	ds_write_b128 v207, v[0:3]
	s_waitcnt vmcnt(1)
	ds_write_b128 v207, v[8:11] offset:18432
	ds_write_b128 v207, v[4:7] offset:9216
	s_waitcnt vmcnt(0)
	ds_write_b128 v207, v[12:15] offset:27648
	s_waitcnt lgkmcnt(0)
	s_barrier
	s_cbranch_vccz .LBB0_547
	s_andn2_b64 vcc, exec, s[8:9]
	s_cbranch_vccnz .LBB0_546
	global_load_dwordx4 v[0:3], v[190:191], off offset:1024 nt
	global_load_dwordx4 v[4:7], v[190:191], off offset:1152 nt
	global_load_dwordx4 v[8:11], v[190:191], off offset:1280 nt
	global_load_dwordx4 v[12:15], v[190:191], off offset:1408 nt

; #define ATT_RANGE(r0, lo, hi) do { int ss_, se_; if ((r0) < TP) { ss_ = (r0) & ~8191; se_ = ss_ + 8192; } else { ss_ = TP + (((r0) - TP) & ~2047); se_ = ss_ + 2048; } \
;         lo = ((r0) - 128 < ss_) ? ((ss_ - ((r0) - 128)) >> 6) : 0; hi = ((r0) + 128 >= se_) ? (((se_ - 64) - ((r0) - 128)) >> 6) : 4; } while (0)
; #define ATT_ISSUE(r0, kb) do { const bf16_t* src_ = proj + (size_t)((r0) - 128 + 64 * (kb) + skey) * DIN + 512 + sdch * 8; \
;         pk[0] = *(const u32x4*)src_; pv[0] = *(const u32x4*)(src_ + 128); pk[1] = *(const u32x4*)(src_ + 64); pv[1] = *(const u32x4*)(src_ + 192); } while (0)
; __device__ __forceinline__ void attn_phase(const Params& p, LAS unsigned char* lds, int G) {
;     ...
;             if (kb < kb_hi) { ATT_ISSUE(row0, kb + 1); }
;             else if (unit + G < T / 64) { int lo2, hi2; ATT_RANGE((unit + G) * 64, lo2, hi2); ATT_ISSUE((unit + G) * 64, lo2); (void)hi2; }
.LBB0_547:
	s_andn2_b64 vcc, exec, s[2:3]
	s_cbranch_vccnz .LBB0_549
	s_waitcnt vmcnt(3)
	v_add_u32_e32 v0, s21, v225
	s_waitcnt vmcnt(0)
	v_mad_i64_i32 v[12:13], s[2:3], v0, s15, v[180:181]
	global_load_dwordx4 v[0:3], v[12:13], off offset:1024 nt
	global_load_dwordx4 v[4:7], v[12:13], off offset:1152 nt
	global_load_dwordx4 v[8:11], v[12:13], off offset:1280 nt
	s_nop 0
	global_load_dwordx4 v[12:15], v[12:13], off offset:1408 nt

; __device__ __forceinline__ float fexp(float x) { return __builtin_amdgcn_exp2f(1.4426950408889634f * x); }
; __device__ __forceinline__ unsigned pk2(float lo, float hi) { return f2bf(lo) | (f2bf(hi) << 16); }
; __device__ __forceinline__ void ret_scan_phase(const Params& p, int G) {
;     ...
;     for (int t = blockIdx.x * NTHR + threadIdx.x; t < 131072; t += nthr) {
;         {
;             const int e4 = t & 4095, sdh = t >> 12, dir = sdh & 1, h = (sdh >> 1) & 3, b = sdh >> 3, c0 = 64 * b;
;             const float Dk = fexp((dir ? p.in[11][h] : p.in[10][h]) * 128.0f);
;             float st[4] = {0.f, 0.f, 0.f, 0.f};
;             for (int sb = 0; sb < 64; sb += 16) {
;                 u32x2 v[16];
; #pragma unroll
;                 for (int i = 0; i < 16; ++i) { const int c = dir ? (c0 + 63 - sb - i) : (c0 + sb + i); v[i] = *(const u32x2*)(kvbuf + ((size_t)(c * 4 + h) * 2 + dir) * 16384 + e4 * 4); }
; #pragma unroll
;                 for (int i = 0; i < 16; ++i) { const int c = dir ? (c0 + 63 - sb - i) : (c0 + sb + i);
;                     u32x2 w; w.x = pk2(st[0], st[1]); w.y = pk2(st[2], st[3]); *(u32x2*)(kvbuf + ((size_t)(c * 4 + h) * 2 + dir) * 16384 + e4 * 4) = w;
.LBB0_636:
	s_waitcnt vmcnt(0)
	v_bfe_u32 v2, v70, 12, 1
	v_bfe_u32 v18, v70, 13, 2
	v_cmp_eq_u32_e32 vcc, 0, v2
	v_lshlrev_b32_e32 v44, 2, v18
	v_lshlrev_b32_e32 v7, 3, v70
	v_cndmask_b32_e32 v1, v71, v72, vcc
	v_cndmask_b32_e32 v0, v73, v74, vcc
	v_lshl_add_u64 v[0:1], v[0:1], 0, v[44:45]
	global_load_dword v0, v[0:1], off nt
	v_ashrrev_i32_e32 v1, 9, v70
	v_lshlrev_b32_e32 v44, 15, v2
	v_and_b32_e32 v19, 0xffffffc0, v1
	v_or_b32_e32 v1, 63, v1
	v_lshl_add_u64 v[2:3], s[8:9], 0, v[44:45]
	v_and_b32_e32 v44, 0x7ff8, v7
	s_mov_b32 s16, -16
	v_mov_b32_e32 v4, 0
	v_mov_b32_e32 v6, 0
	v_mov_b32_e32 v5, v45
	v_add_u32_e32 v20, -15, v1
	v_lshl_add_u64 v[2:3], v[2:3], 0, v[44:45]
	v_mov_b32_e32 v7, v45
	s_waitcnt vmcnt(0)
	v_mul_f32_e32 v0, 0x43000000, v0
	v_mul_f32_e32 v0, 0x3fb8aa3b, v0
	v_exp_f32_e32 v0, v0
	s_nop 0
	v_mov_b32_e32 v1, v0
.LBB0_637:
	v_add_u32_e32 v9, s16, v19
	v_add_u32_e32 v8, 15, v20
	v_add_u32_e32 v31, 16, v9
	v_add_u32_e32 v10, 14, v20
	v_add_u32_e32 v11, 13, v20
	v_add_u32_e32 v12, 12, v20
	v_add_u32_e32 v13, 11, v20
	v_add_u32_e32 v14, 10, v20
	v_add_u32_e32 v15, 9, v20
	v_add_u32_e32 v16, 8, v20
	v_add_u32_e32 v17, 7, v20
	v_add_u32_e32 v21, 6, v20
	v_add_u32_e32 v22, 5, v20
	v_add_u32_e32 v23, 4, v20
	v_add_u32_e32 v24, 3, v20
	v_add_u32_e32 v25, 2, v20
	v_add_u32_e32 v26, 1, v20
	v_and_b32_sdwa v28, v4, v75 dst_sel:DWORD dst_unused:UNUSED_PAD src0_sel:WORD_1 src1_sel:DWORD
	v_and_b32_sdwa v29, v7, v75 dst_sel:DWORD dst_unused:UNUSED_PAD src0_sel:WORD_1 src1_sel:DWORD
	v_and_b32_sdwa v30, v6, v75 dst_sel:DWORD dst_unused:UNUSED_PAD src0_sel:WORD_1 src1_sel:DWORD
	v_add_u32_e32 v32, 17, v9
	v_add_u32_e32 v33, 18, v9
	v_add_u32_e32 v34, 19, v9
	v_add_u32_e32 v35, 20, v9
	v_add_u32_e32 v36, 21, v9
	v_add_u32_e32 v37, 22, v9
	v_add_u32_e32 v38, 23, v9
	v_add_u32_e32 v39, 24, v9
	v_add_u32_e32 v40, 25, v9
	v_add_u32_e32 v41, 26, v9
	v_add_u32_e32 v42, 27, v9
	v_add_u32_e32 v43, 28, v9
	v_add_u32_e32 v44, 29, v9
	v_add_u32_e32 v46, 30, v9
	v_add_u32_e32 v9, 31, v9
	v_cndmask_b32_e32 v8, v8, v31, vcc
	v_and_b32_sdwa v27, v5, v75 dst_sel:DWORD dst_unused:UNUSED_PAD src0_sel:WORD_1 src1_sel:DWORD
	v_add3_u32 v48, v4, v28, s13
	v_add3_u32 v28, v7, v29, s13
	v_add3_u32 v29, v6, v30, s13
	v_cndmask_b32_e32 v10, v10, v32, vcc
	v_cndmask_b32_e32 v11, v11, v33, vcc
	v_cndmask_b32_e32 v30, v12, v34, vcc
	v_cndmask_b32_e32 v13, v13, v35, vcc
	v_cndmask_b32_e32 v31, v14, v36, vcc
	v_cndmask_b32_e32 v15, v15, v37, vcc
	v_cndmask_b32_e32 v32, v16, v38, vcc
	v_cndmask_b32_e32 v17, v17, v39, vcc
	v_cndmask_b32_e32 v21, v21, v40, vcc
	v_cndmask_b32_e32 v33, v22, v41, vcc
	v_cndmask_b32_e32 v23, v23, v42, vcc
	v_cndmask_b32_e32 v35, v24, v43, vcc
	v_cndmask_b32_e32 v25, v25, v44, vcc
	v_cndmask_b32_e32 v37, v26, v46, vcc
	v_cndmask_b32_e32 v9, v20, v9, vcc
	v_lshl_or_b32 v8, v8, 2, v18
	v_add3_u32 v27, v5, v27, s13
	v_and_b32_e32 v39, 0xffff0000, v28
	v_and_b32_e32 v29, 0xffff0000, v29
	v_lshl_or_b32 v10, v10, 2, v18
	v_lshl_or_b32 v12, v11, 2, v18
	v_lshl_or_b32 v14, v30, 2, v18
	v_lshl_or_b32 v16, v13, 2, v18
	v_lshl_or_b32 v22, v31, 2, v18
	v_lshl_or_b32 v24, v15, 2, v18
	v_lshl_or_b32 v26, v32, 2, v18
	v_lshl_or_b32 v28, v17, 2, v18
	v_lshl_or_b32 v30, v21, 2, v18
	v_lshl_or_b32 v32, v33, 2, v18
	v_lshl_or_b32 v34, v23, 2, v18
	v_lshl_or_b32 v36, v35, 2, v18
	v_lshl_or_b32 v38, v25, 2, v18
	v_lshl_or_b32 v40, v37, 2, v18
	v_lshl_or_b32 v42, v9, 2, v18
	v_ashrrev_i32_e32 v9, 31, v8
	v_or_b32_sdwa v47, v39, v27 dst_sel:DWORD dst_unused:UNUSED_PAD src0_sel:DWORD src1_sel:WORD_1
	v_or_b32_sdwa v46, v29, v48 dst_sel:DWORD dst_unused:UNUSED_PAD src0_sel:DWORD src1_sel:WORD_1
	v_ashrrev_i32_e32 v11, 31, v10
	v_ashrrev_i32_e32 v13, 31, v12
	v_ashrrev_i32_e32 v15, 31, v14
	v_ashrrev_i32_e32 v17, 31, v16
	v_ashrrev_i32_e32 v23, 31, v22
	v_ashrrev_i32_e32 v25, 31, v24
	v_ashrrev_i32_e32 v27, 31, v26
	v_ashrrev_i32_e32 v29, 31, v28
	v_ashrrev_i32_e32 v31, 31, v30
	v_ashrrev_i32_e32 v33, 31, v32
	v_ashrrev_i32_e32 v35, 31, v34
	v_ashrrev_i32_e32 v37, 31, v36
	v_ashrrev_i32_e32 v39, 31, v38
	v_ashrrev_i32_e32 v41, 31, v40
	v_ashrrev_i32_e32 v43, 31, v42
	v_lshlrev_b64 v[8:9], 16, v[8:9]
	v_lshlrev_b64 v[10:11], 16, v[10:11]
	v_lshlrev_b64 v[12:13], 16, v[12:13]
	v_lshlrev_b64 v[14:15], 16, v[14:15]
	v_lshlrev_b64 v[16:17], 16, v[16:17]
	v_lshlrev_b64 v[22:23], 16, v[22:23]
	v_lshlrev_b64 v[24:25], 16, v[24:25]
	v_lshlrev_b64 v[26:27], 16, v[26:27]
	v_lshlrev_b64 v[28:29], 16, v[28:29]
	v_lshlrev_b64 v[30:31], 16, v[30:31]
	v_lshlrev_b64 v[32:33], 16, v[32:33]
	v_lshlrev_b64 v[34:35], 16, v[34:35]
	v_lshlrev_b64 v[36:37], 16, v[36:37]
	v_lshlrev_b64 v[38:39], 16, v[38:39]
	v_lshlrev_b64 v[40:41], 16, v[40:41]
	v_lshlrev_b64 v[42:43], 16, v[42:43]
	v_lshl_add_u64 v[48:49], v[2:3], 0, v[8:9]
	v_lshl_add_u64 v[50:51], v[2:3], 0, v[10:11]
	v_lshl_add_u64 v[52:53], v[2:3], 0, v[12:13]
	v_lshl_add_u64 v[54:55], v[2:3], 0, v[14:15]
	v_lshl_add_u64 v[56:57], v[2:3], 0, v[16:17]
	v_lshl_add_u64 v[22:23], v[2:3], 0, v[22:23]
	v_lshl_add_u64 v[24:25], v[2:3], 0, v[24:25]
	v_lshl_add_u64 v[26:27], v[2:3], 0, v[26:27]
	v_lshl_add_u64 v[28:29], v[2:3], 0, v[28:29]
	v_lshl_add_u64 v[30:31], v[2:3], 0, v[30:31]
	v_lshl_add_u64 v[32:33], v[2:3], 0, v[32:33]
	v_lshl_add_u64 v[16:17], v[2:3], 0, v[34:35]
	v_lshl_add_u64 v[14:15], v[2:3], 0, v[36:37]
	v_lshl_add_u64 v[12:13], v[2:3], 0, v[38:39]
	v_lshl_add_u64 v[8:9], v[2:3], 0, v[40:41]
	v_lshl_add_u64 v[10:11], v[2:3], 0, v[42:43]
	global_load_dwordx2 v[34:35], v[48:49], off nt
	global_load_dwordx2 v[36:37], v[50:51], off nt
	global_load_dwordx2 v[38:39], v[52:53], off nt
	global_load_dwordx2 v[40:41], v[54:55], off nt
	global_load_dwordx2 v[42:43], v[56:57], off nt
	global_load_dwordx2 v[58:59], v[22:23], off nt
	global_load_dwordx2 v[60:61], v[24:25], off nt
	global_load_dwordx2 v[62:63], v[26:27], off nt
	global_load_dwordx2 v[64:65], v[28:29], off nt
	global_load_dwordx2 v[66:67], v[16:17], off nt
	global_load_dwordx2 v[68:69], v[30:31], off nt
	global_load_dwordx2 v[76:77], v[32:33], off nt
	global_load_dwordx2 v[82:83], v[14:15], off nt
	global_load_dwordx2 v[84:85], v[12:13], off nt
	global_load_dwordx2 v[86:87], v[8:9], off nt
	global_load_dwordx2 v[88:89], v[10:11], off nt
	s_add_i32 s16, s16, 16
	global_store_dwordx2 v[48:49], v[46:47], off
	s_cmp_gt_u32 s16, 47
	v_add_u32_e32 v20, -16, v20
	s_waitcnt vmcnt(16)
; __device__ __forceinline__ unsigned pk2(float lo, float hi) { return f2bf(lo) | (f2bf(hi) << 16); }
; __device__ __forceinline__ void ret_scan_phase(const Params& p, int G) {
;     ...
;                 for (int i = 0; i < 16; ++i) { const int c = dir ? (c0 + 63 - sb - i) : (c0 + sb + i);
;                     u32x2 w; w.x = pk2(st[0], st[1]); w.y = pk2(st[2], st[3]); *(u32x2*)(kvbuf + ((size_t)(c * 4 + h) * 2 + dir) * 16384 + e4 * 4) = w;
;                     st[0] = st[0] * Dk + bf2f((unsigned short)(v[i].x & 0xffffu)); st[1] = st[1] * Dk + bf2f((unsigned short)(v[i].x >> 16));
;                     st[2] = st[2] * Dk + bf2f((unsigned short)(v[i].y & 0xffffu)); st[3] = st[3] * Dk + bf2f((unsigned short)(v[i].y >> 16)); }
	v_lshlrev_b32_e32 v47, 16, v35
	v_lshlrev_b32_e32 v46, 16, v34
	v_and_b32_e32 v35, 0xffff0000, v35
	v_and_b32_e32 v34, 0xffff0000, v34
	s_waitcnt vmcnt(15)
	v_lshlrev_b32_e32 v49, 16, v37
	v_lshlrev_b32_e32 v48, 16, v36
	v_and_b32_e32 v37, 0xffff0000, v37
	v_and_b32_e32 v36, 0xffff0000, v36
	v_pk_fma_f32 v[4:5], v[0:1], v[4:5], v[46:47]
	v_pk_fma_f32 v[6:7], v[0:1], v[6:7], v[34:35]
	s_waitcnt vmcnt(14)
	v_lshlrev_b32_e32 v91, 16, v39
	v_lshlrev_b32_e32 v90, 16, v38
	v_and_b32_e32 v39, 0xffff0000, v39
	v_and_b32_e32 v38, 0xffff0000, v38
	v_and_b32_sdwa v21, v5, v75 dst_sel:DWORD dst_unused:UNUSED_PAD src0_sel:WORD_1 src1_sel:DWORD
	v_and_b32_sdwa v44, v4, v75 dst_sel:DWORD dst_unused:UNUSED_PAD src0_sel:WORD_1 src1_sel:DWORD
	v_and_b32_sdwa v46, v7, v75 dst_sel:DWORD dst_unused:UNUSED_PAD src0_sel:WORD_1 src1_sel:DWORD
	v_and_b32_sdwa v47, v6, v75 dst_sel:DWORD dst_unused:UNUSED_PAD src0_sel:WORD_1 src1_sel:DWORD
	v_pk_fma_f32 v[34:35], v[0:1], v[4:5], v[48:49]
	v_pk_fma_f32 v[36:37], v[0:1], v[6:7], v[36:37]
	s_waitcnt vmcnt(13)
	v_lshlrev_b32_e32 v93, 16, v41
	v_lshlrev_b32_e32 v92, 16, v40
	v_and_b32_e32 v41, 0xffff0000, v41
	v_and_b32_e32 v40, 0xffff0000, v40
	s_waitcnt vmcnt(5)
	v_and_b32_e32 v107, 0xffff0000, v76
	v_lshlrev_b32_e32 v106, 16, v76
	v_and_b32_e32 v109, 0xffff0000, v77
	v_lshlrev_b32_e32 v108, 16, v77
	v_and_b32_e32 v77, 0xffff0000, v66
	v_lshlrev_b32_e32 v76, 16, v66
	s_waitcnt vmcnt(4)
	v_and_b32_e32 v111, 0xffff0000, v82
	v_lshlrev_b32_e32 v110, 16, v82
	s_waitcnt vmcnt(3)
	v_and_b32_e32 v113, 0xffff0000, v84
	v_lshlrev_b32_e32 v112, 16, v84
	s_waitcnt vmcnt(2)
	v_and_b32_e32 v115, 0xffff0000, v86
	v_lshlrev_b32_e32 v114, 16, v86
	s_waitcnt vmcnt(1)
	v_and_b32_e32 v117, 0xffff0000, v88
	v_lshlrev_b32_e32 v116, 16, v88
	v_and_b32_e32 v119, 0xffff0000, v67
	v_lshlrev_b32_e32 v118, 16, v67
	v_and_b32_e32 v67, 0xffff0000, v83
	v_lshlrev_b32_e32 v66, 16, v83
	v_and_b32_e32 v83, 0xffff0000, v85
	v_lshlrev_b32_e32 v82, 16, v85
	v_and_b32_e32 v85, 0xffff0000, v87
	v_lshlrev_b32_e32 v84, 16, v87
	v_and_b32_e32 v87, 0xffff0000, v89
	v_lshlrev_b32_e32 v86, 16, v89
	v_add3_u32 v44, v4, v44, s13
	v_add3_u32 v21, v5, v21, s13
	v_add3_u32 v46, v7, v46, s13
	v_add3_u32 v47, v6, v47, s13
	v_and_b32_sdwa v48, v35, v75 dst_sel:DWORD dst_unused:UNUSED_PAD src0_sel:WORD_1 src1_sel:DWORD
	v_and_b32_sdwa v49, v34, v75 dst_sel:DWORD dst_unused:UNUSED_PAD src0_sel:WORD_1 src1_sel:DWORD
	v_and_b32_sdwa v88, v37, v75 dst_sel:DWORD dst_unused:UNUSED_PAD src0_sel:WORD_1 src1_sel:DWORD
	v_and_b32_sdwa v89, v36, v75 dst_sel:DWORD dst_unused:UNUSED_PAD src0_sel:WORD_1 src1_sel:DWORD
	v_pk_fma_f32 v[4:5], v[0:1], v[34:35], v[90:91]
	v_pk_fma_f32 v[6:7], v[0:1], v[36:37], v[38:39]
	v_lshlrev_b32_e32 v95, 16, v43
	v_lshlrev_b32_e32 v94, 16, v42
	v_and_b32_e32 v43, 0xffff0000, v43
	v_and_b32_e32 v42, 0xffff0000, v42
	v_and_b32_e32 v38, 0xffff0000, v46
	v_and_b32_e32 v46, 0xffff0000, v47
	v_add3_u32 v47, v34, v49, s13
	v_add3_u32 v48, v35, v48, s13
	v_add3_u32 v49, v37, v88, s13
	v_add3_u32 v88, v36, v89, s13
	v_and_b32_sdwa v89, v5, v75 dst_sel:DWORD dst_unused:UNUSED_PAD src0_sel:WORD_1 src1_sel:DWORD
	v_and_b32_sdwa v90, v4, v75 dst_sel:DWORD dst_unused:UNUSED_PAD src0_sel:WORD_1 src1_sel:DWORD
	v_and_b32_sdwa v91, v7, v75 dst_sel:DWORD dst_unused:UNUSED_PAD src0_sel:WORD_1 src1_sel:DWORD
	v_and_b32_sdwa v120, v6, v75 dst_sel:DWORD dst_unused:UNUSED_PAD src0_sel:WORD_1 src1_sel:DWORD
	v_pk_fma_f32 v[34:35], v[0:1], v[4:5], v[92:93]
	v_pk_fma_f32 v[36:37], v[0:1], v[6:7], v[40:41]
	v_lshlrev_b32_e32 v97, 16, v59
	v_lshlrev_b32_e32 v96, 16, v58
	v_and_b32_e32 v59, 0xffff0000, v59
	v_and_b32_e32 v58, 0xffff0000, v58
	v_or_b32_sdwa v39, v21, v38 dst_sel:DWORD dst_unused:UNUSED_PAD src0_sel:WORD_1 src1_sel:DWORD
	v_or_b32_sdwa v38, v44, v46 dst_sel:DWORD dst_unused:UNUSED_PAD src0_sel:WORD_1 src1_sel:DWORD
	v_and_b32_e32 v21, 0xffff0000, v49
	v_and_b32_e32 v40, 0xffff0000, v88
	v_add3_u32 v41, v4, v90, s13
	v_add3_u32 v44, v5, v89, s13
	v_add3_u32 v46, v7, v91, s13
	v_add3_u32 v49, v6, v120, s13
	v_and_b32_sdwa v88, v35, v75 dst_sel:DWORD dst_unused:UNUSED_PAD src0_sel:WORD_1 src1_sel:DWORD
	v_and_b32_sdwa v89, v34, v75 dst_sel:DWORD dst_unused:UNUSED_PAD src0_sel:WORD_1 src1_sel:DWORD
	v_and_b32_sdwa v90, v37, v75 dst_sel:DWORD dst_unused:UNUSED_PAD src0_sel:WORD_1 src1_sel:DWORD
	v_and_b32_sdwa v91, v36, v75 dst_sel:DWORD dst_unused:UNUSED_PAD src0_sel:WORD_1 src1_sel:DWORD
	v_pk_fma_f32 v[4:5], v[0:1], v[34:35], v[94:95]
	v_pk_fma_f32 v[6:7], v[0:1], v[36:37], v[42:43]
	v_lshlrev_b32_e32 v99, 16, v61
	v_lshlrev_b32_e32 v98, 16, v60
	v_and_b32_e32 v61, 0xffff0000, v61
	v_and_b32_e32 v60, 0xffff0000, v60
	global_store_dwordx2 v[50:51], v[38:39], off
	v_or_b32_sdwa v39, v48, v21 dst_sel:DWORD dst_unused:UNUSED_PAD src0_sel:WORD_1 src1_sel:DWORD
	v_or_b32_sdwa v38, v47, v40 dst_sel:DWORD dst_unused:UNUSED_PAD src0_sel:WORD_1 src1_sel:DWORD
	v_and_b32_e32 v21, 0xffff0000, v46
	v_and_b32_e32 v40, 0xffff0000, v49
	v_add3_u32 v42, v34, v89, s13
	v_add3_u32 v43, v35, v88, s13
	v_add3_u32 v46, v37, v90, s13
	v_add3_u32 v47, v36, v91, s13
	v_and_b32_sdwa v48, v5, v75 dst_sel:DWORD dst_unused:UNUSED_PAD src0_sel:WORD_1 src1_sel:DWORD
	v_and_b32_sdwa v49, v4, v75 dst_sel:DWORD dst_unused:UNUSED_PAD src0_sel:WORD_1 src1_sel:DWORD
	v_and_b32_sdwa v50, v7, v75 dst_sel:DWORD dst_unused:UNUSED_PAD src0_sel:WORD_1 src1_sel:DWORD
	v_and_b32_sdwa v51, v6, v75 dst_sel:DWORD dst_unused:UNUSED_PAD src0_sel:WORD_1 src1_sel:DWORD
	v_pk_fma_f32 v[34:35], v[0:1], v[4:5], v[96:97]
	v_pk_fma_f32 v[36:37], v[0:1], v[6:7], v[58:59]
	v_lshlrev_b32_e32 v101, 16, v63
; __device__ __forceinline__ unsigned pk2(float lo, float hi) { return f2bf(lo) | (f2bf(hi) << 16); }
; __device__ __forceinline__ void ret_scan_phase(const Params& p, int G) {
;     ...
;                 for (int i = 0; i < 16; ++i) { const int c = dir ? (c0 + 63 - sb - i) : (c0 + sb + i);
;                     u32x2 w; w.x = pk2(st[0], st[1]); w.y = pk2(st[2], st[3]); *(u32x2*)(kvbuf + ((size_t)(c * 4 + h) * 2 + dir) * 16384 + e4 * 4) = w;
;                     st[0] = st[0] * Dk + bf2f((unsigned short)(v[i].x & 0xffffu)); st[1] = st[1] * Dk + bf2f((unsigned short)(v[i].x >> 16));
;                     st[2] = st[2] * Dk + bf2f((unsigned short)(v[i].y & 0xffffu)); st[3] = st[3] * Dk + bf2f((unsigned short)(v[i].y >> 16)); }
	v_lshlrev_b32_e32 v100, 16, v62
	v_and_b32_e32 v63, 0xffff0000, v63
	v_and_b32_e32 v62, 0xffff0000, v62
	global_store_dwordx2 v[52:53], v[38:39], off
	v_or_b32_sdwa v39, v44, v21 dst_sel:DWORD dst_unused:UNUSED_PAD src0_sel:WORD_1 src1_sel:DWORD
	v_or_b32_sdwa v38, v41, v40 dst_sel:DWORD dst_unused:UNUSED_PAD src0_sel:WORD_1 src1_sel:DWORD
	v_and_b32_e32 v21, 0xffff0000, v46
	v_and_b32_e32 v40, 0xffff0000, v47
	v_add3_u32 v41, v4, v49, s13
	v_add3_u32 v44, v5, v48, s13
	v_add3_u32 v46, v7, v50, s13
	v_add3_u32 v47, v6, v51, s13
	v_and_b32_sdwa v48, v35, v75 dst_sel:DWORD dst_unused:UNUSED_PAD src0_sel:WORD_1 src1_sel:DWORD
	v_and_b32_sdwa v49, v34, v75 dst_sel:DWORD dst_unused:UNUSED_PAD src0_sel:WORD_1 src1_sel:DWORD
	v_and_b32_sdwa v50, v37, v75 dst_sel:DWORD dst_unused:UNUSED_PAD src0_sel:WORD_1 src1_sel:DWORD
	v_and_b32_sdwa v51, v36, v75 dst_sel:DWORD dst_unused:UNUSED_PAD src0_sel:WORD_1 src1_sel:DWORD
	v_pk_fma_f32 v[4:5], v[0:1], v[34:35], v[98:99]
	v_pk_fma_f32 v[6:7], v[0:1], v[36:37], v[60:61]
	v_lshlrev_b32_e32 v103, 16, v65
	v_lshlrev_b32_e32 v102, 16, v64
	v_and_b32_e32 v65, 0xffff0000, v65
	v_and_b32_e32 v64, 0xffff0000, v64
	global_store_dwordx2 v[54:55], v[38:39], off
	v_or_b32_sdwa v39, v43, v21 dst_sel:DWORD dst_unused:UNUSED_PAD src0_sel:WORD_1 src1_sel:DWORD
	v_or_b32_sdwa v38, v42, v40 dst_sel:DWORD dst_unused:UNUSED_PAD src0_sel:WORD_1 src1_sel:DWORD
	v_and_b32_e32 v21, 0xffff0000, v46
	v_and_b32_e32 v40, 0xffff0000, v47
	v_add3_u32 v42, v34, v49, s13
	v_add3_u32 v43, v35, v48, s13
	v_add3_u32 v46, v37, v50, s13
	v_add3_u32 v47, v36, v51, s13
	v_and_b32_sdwa v48, v5, v75 dst_sel:DWORD dst_unused:UNUSED_PAD src0_sel:WORD_1 src1_sel:DWORD
	v_and_b32_sdwa v49, v4, v75 dst_sel:DWORD dst_unused:UNUSED_PAD src0_sel:WORD_1 src1_sel:DWORD
	v_and_b32_sdwa v50, v7, v75 dst_sel:DWORD dst_unused:UNUSED_PAD src0_sel:WORD_1 src1_sel:DWORD
	v_and_b32_sdwa v51, v6, v75 dst_sel:DWORD dst_unused:UNUSED_PAD src0_sel:WORD_1 src1_sel:DWORD
	v_pk_fma_f32 v[34:35], v[0:1], v[4:5], v[100:101]
	v_pk_fma_f32 v[36:37], v[0:1], v[6:7], v[62:63]
	v_lshlrev_b32_e32 v105, 16, v69
	v_lshlrev_b32_e32 v104, 16, v68
	v_and_b32_e32 v69, 0xffff0000, v69
	v_and_b32_e32 v68, 0xffff0000, v68
	global_store_dwordx2 v[56:57], v[38:39], off
	v_or_b32_sdwa v39, v44, v21 dst_sel:DWORD dst_unused:UNUSED_PAD src0_sel:WORD_1 src1_sel:DWORD
	v_or_b32_sdwa v38, v41, v40 dst_sel:DWORD dst_unused:UNUSED_PAD src0_sel:WORD_1 src1_sel:DWORD
	v_and_b32_e32 v21, 0xffff0000, v46
	v_and_b32_e32 v40, 0xffff0000, v47
	v_add3_u32 v41, v4, v49, s13
	v_add3_u32 v44, v5, v48, s13
	v_add3_u32 v46, v7, v50, s13
	v_add3_u32 v47, v6, v51, s13
	v_and_b32_sdwa v48, v35, v75 dst_sel:DWORD dst_unused:UNUSED_PAD src0_sel:WORD_1 src1_sel:DWORD
	v_and_b32_sdwa v49, v34, v75 dst_sel:DWORD dst_unused:UNUSED_PAD src0_sel:WORD_1 src1_sel:DWORD
	v_and_b32_sdwa v50, v37, v75 dst_sel:DWORD dst_unused:UNUSED_PAD src0_sel:WORD_1 src1_sel:DWORD
	v_and_b32_sdwa v51, v36, v75 dst_sel:DWORD dst_unused:UNUSED_PAD src0_sel:WORD_1 src1_sel:DWORD
	v_pk_fma_f32 v[4:5], v[0:1], v[34:35], v[102:103]
	v_pk_fma_f32 v[6:7], v[0:1], v[36:37], v[64:65]
	global_store_dwordx2 v[22:23], v[38:39], off
	v_or_b32_sdwa v23, v43, v21 dst_sel:DWORD dst_unused:UNUSED_PAD src0_sel:WORD_1 src1_sel:DWORD
	v_or_b32_sdwa v22, v42, v40 dst_sel:DWORD dst_unused:UNUSED_PAD src0_sel:WORD_1 src1_sel:DWORD
	v_and_b32_e32 v21, 0xffff0000, v46
	v_and_b32_e32 v38, 0xffff0000, v47
	v_add3_u32 v39, v34, v49, s13
	v_add3_u32 v40, v35, v48, s13
	v_add3_u32 v42, v37, v50, s13
	v_add3_u32 v43, v36, v51, s13
	v_and_b32_sdwa v46, v5, v75 dst_sel:DWORD dst_unused:UNUSED_PAD src0_sel:WORD_1 src1_sel:DWORD
	v_and_b32_sdwa v47, v4, v75 dst_sel:DWORD dst_unused:UNUSED_PAD src0_sel:WORD_1 src1_sel:DWORD
	v_and_b32_sdwa v48, v7, v75 dst_sel:DWORD dst_unused:UNUSED_PAD src0_sel:WORD_1 src1_sel:DWORD
	v_and_b32_sdwa v49, v6, v75 dst_sel:DWORD dst_unused:UNUSED_PAD src0_sel:WORD_1 src1_sel:DWORD
	v_pk_fma_f32 v[34:35], v[0:1], v[4:5], v[104:105]
	v_pk_fma_f32 v[36:37], v[0:1], v[6:7], v[68:69]
	global_store_dwordx2 v[24:25], v[22:23], off
	v_or_b32_sdwa v23, v44, v21 dst_sel:DWORD dst_unused:UNUSED_PAD src0_sel:WORD_1 src1_sel:DWORD
	v_or_b32_sdwa v22, v41, v38 dst_sel:DWORD dst_unused:UNUSED_PAD src0_sel:WORD_1 src1_sel:DWORD
	v_and_b32_e32 v21, 0xffff0000, v42
	v_and_b32_e32 v24, 0xffff0000, v43
	v_add3_u32 v25, v4, v47, s13
	v_add3_u32 v38, v5, v46, s13
	v_add3_u32 v41, v7, v48, s13
	v_add3_u32 v42, v6, v49, s13
	v_and_b32_sdwa v46, v37, v75 dst_sel:DWORD dst_unused:UNUSED_PAD src0_sel:WORD_1 src1_sel:DWORD
	v_and_b32_sdwa v47, v36, v75 dst_sel:DWORD dst_unused:UNUSED_PAD src0_sel:WORD_1 src1_sel:DWORD
	v_mov_b32_e32 v4, v34
	v_mov_b32_e32 v5, v36
	v_and_b32_sdwa v43, v35, v75 dst_sel:DWORD dst_unused:UNUSED_PAD src0_sel:WORD_1 src1_sel:DWORD
	v_and_b32_sdwa v44, v34, v75 dst_sel:DWORD dst_unused:UNUSED_PAD src0_sel:WORD_1 src1_sel:DWORD
	global_store_dwordx2 v[26:27], v[22:23], off
	v_or_b32_sdwa v7, v40, v21 dst_sel:DWORD dst_unused:UNUSED_PAD src0_sel:WORD_1 src1_sel:DWORD
	v_or_b32_sdwa v6, v39, v24 dst_sel:DWORD dst_unused:UNUSED_PAD src0_sel:WORD_1 src1_sel:DWORD
	v_and_b32_e32 v21, 0xffff0000, v41
	v_and_b32_e32 v22, 0xffff0000, v42
	v_add3_u32 v23, v37, v46, s13
	v_add3_u32 v24, v36, v47, s13
	v_mov_b32_e32 v36, v35
	v_pk_fma_f32 v[4:5], v[0:1], v[4:5], v[106:107]
	v_add3_u32 v26, v34, v44, s13
	v_add3_u32 v27, v35, v43, s13
	global_store_dwordx2 v[28:29], v[6:7], off
	v_or_b32_sdwa v7, v38, v21 dst_sel:DWORD dst_unused:UNUSED_PAD src0_sel:WORD_1 src1_sel:DWORD
	v_or_b32_sdwa v6, v25, v22 dst_sel:DWORD dst_unused:UNUSED_PAD src0_sel:WORD_1 src1_sel:DWORD
; __device__ __forceinline__ unsigned pk2(float lo, float hi) { return f2bf(lo) | (f2bf(hi) << 16); }
; __device__ __forceinline__ void ret_scan_phase(const Params& p, int G) {
;     ...
;                 for (int i = 0; i < 16; ++i) { const int c = dir ? (c0 + 63 - sb - i) : (c0 + sb + i);
;                     u32x2 w; w.x = pk2(st[0], st[1]); w.y = pk2(st[2], st[3]); *(u32x2*)(kvbuf + ((size_t)(c * 4 + h) * 2 + dir) * 16384 + e4 * 4) = w;
;                     st[0] = st[0] * Dk + bf2f((unsigned short)(v[i].x & 0xffffu)); st[1] = st[1] * Dk + bf2f((unsigned short)(v[i].x >> 16));
;                     st[2] = st[2] * Dk + bf2f((unsigned short)(v[i].y & 0xffffu)); st[3] = st[3] * Dk + bf2f((unsigned short)(v[i].y >> 16)); }
	v_and_b32_e32 v21, 0xffff0000, v23
	v_and_b32_e32 v28, 0xffff0000, v24
	v_pk_fma_f32 v[22:23], v[0:1], v[4:5], v[76:77]
	v_pk_fma_f32 v[24:25], v[0:1], v[36:37], v[108:109]
	v_and_b32_sdwa v29, v4, v75 dst_sel:DWORD dst_unused:UNUSED_PAD src0_sel:WORD_1 src1_sel:DWORD
	v_and_b32_sdwa v34, v5, v75 dst_sel:DWORD dst_unused:UNUSED_PAD src0_sel:WORD_1 src1_sel:DWORD
	global_store_dwordx2 v[30:31], v[6:7], off
	v_or_b32_sdwa v7, v27, v21 dst_sel:DWORD dst_unused:UNUSED_PAD src0_sel:WORD_1 src1_sel:DWORD
	v_or_b32_sdwa v6, v26, v28 dst_sel:DWORD dst_unused:UNUSED_PAD src0_sel:WORD_1 src1_sel:DWORD
	v_pk_fma_f32 v[26:27], v[0:1], v[22:23], v[110:111]
	v_add3_u32 v28, v4, v29, s13
	v_and_b32_sdwa v29, v25, v75 dst_sel:DWORD dst_unused:UNUSED_PAD src0_sel:WORD_1 src1_sel:DWORD
	v_add3_u32 v30, v5, v34, s13
	v_pk_fma_f32 v[4:5], v[0:1], v[24:25], v[118:119]
	v_and_b32_sdwa v31, v22, v75 dst_sel:DWORD dst_unused:UNUSED_PAD src0_sel:WORD_1 src1_sel:DWORD
	v_and_b32_sdwa v34, v23, v75 dst_sel:DWORD dst_unused:UNUSED_PAD src0_sel:WORD_1 src1_sel:DWORD
	v_and_b32_sdwa v21, v24, v75 dst_sel:DWORD dst_unused:UNUSED_PAD src0_sel:WORD_1 src1_sel:DWORD
	global_store_dwordx2 v[32:33], v[6:7], off
	v_pk_fma_f32 v[6:7], v[0:1], v[26:27], v[112:113]
	v_add3_u32 v29, v25, v29, s13
	v_and_b32_e32 v30, 0xffff0000, v30
	v_add3_u32 v31, v22, v31, s13
	v_and_b32_sdwa v33, v5, v75 dst_sel:DWORD dst_unused:UNUSED_PAD src0_sel:WORD_1 src1_sel:DWORD
	v_add3_u32 v34, v23, v34, s13
	v_pk_fma_f32 v[22:23], v[0:1], v[4:5], v[66:67]
	v_and_b32_sdwa v35, v26, v75 dst_sel:DWORD dst_unused:UNUSED_PAD src0_sel:WORD_1 src1_sel:DWORD
	v_and_b32_sdwa v36, v27, v75 dst_sel:DWORD dst_unused:UNUSED_PAD src0_sel:WORD_1 src1_sel:DWORD
	v_add3_u32 v21, v24, v21, s13
	v_and_b32_sdwa v32, v4, v75 dst_sel:DWORD dst_unused:UNUSED_PAD src0_sel:WORD_1 src1_sel:DWORD
	v_and_b32_e32 v29, 0xffff0000, v29
	v_or_b32_sdwa v28, v28, v30 dst_sel:DWORD dst_unused:UNUSED_PAD src0_sel:WORD_1 src1_sel:DWORD
	v_add3_u32 v30, v5, v33, s13
	v_and_b32_e32 v33, 0xffff0000, v34
	v_and_b32_sdwa v34, v22, v75 dst_sel:DWORD dst_unused:UNUSED_PAD src0_sel:WORD_1 src1_sel:DWORD
	v_add3_u32 v35, v26, v35, s13
	v_and_b32_sdwa v37, v23, v75 dst_sel:DWORD dst_unused:UNUSED_PAD src0_sel:WORD_1 src1_sel:DWORD
	v_add3_u32 v36, v27, v36, s13
	v_pk_fma_f32 v[26:27], v[0:1], v[22:23], v[82:83]
	v_and_b32_sdwa v38, v6, v75 dst_sel:DWORD dst_unused:UNUSED_PAD src0_sel:WORD_1 src1_sel:DWORD
	v_pk_fma_f32 v[24:25], v[0:1], v[6:7], v[114:115]
	v_add3_u32 v32, v4, v32, s13
	v_and_b32_sdwa v39, v7, v75 dst_sel:DWORD dst_unused:UNUSED_PAD src0_sel:WORD_1 src1_sel:DWORD
	v_or_b32_sdwa v29, v21, v29 dst_sel:DWORD dst_unused:UNUSED_PAD src0_sel:WORD_1 src1_sel:DWORD
	v_and_b32_e32 v21, 0xffff0000, v30
	v_or_b32_sdwa v30, v31, v33 dst_sel:DWORD dst_unused:UNUSED_PAD src0_sel:WORD_1 src1_sel:DWORD
	v_add3_u32 v33, v22, v34, s13
	v_add3_u32 v34, v23, v37, s13
	v_and_b32_e32 v36, 0xffff0000, v36
	v_add3_u32 v38, v6, v38, s13
	v_and_b32_sdwa v6, v27, v75 dst_sel:DWORD dst_unused:UNUSED_PAD src0_sel:WORD_1 src1_sel:DWORD
	v_pk_fma_f32 v[22:23], v[0:1], v[26:27], v[84:85]
	v_and_b32_sdwa v37, v26, v75 dst_sel:DWORD dst_unused:UNUSED_PAD src0_sel:WORD_1 src1_sel:DWORD
	v_add3_u32 v7, v7, v39, s13
	v_and_b32_sdwa v40, v25, v75 dst_sel:DWORD dst_unused:UNUSED_PAD src0_sel:WORD_1 src1_sel:DWORD
	v_or_b32_sdwa v31, v32, v21 dst_sel:DWORD dst_unused:UNUSED_PAD src0_sel:WORD_1 src1_sel:DWORD
	v_and_b32_e32 v21, 0xffff0000, v34
	v_or_b32_sdwa v32, v35, v36 dst_sel:DWORD dst_unused:UNUSED_PAD src0_sel:WORD_1 src1_sel:DWORD
	v_add3_u32 v27, v27, v6, s13
	v_and_b32_sdwa v36, v23, v75 dst_sel:DWORD dst_unused:UNUSED_PAD src0_sel:WORD_1 src1_sel:DWORD
	v_pk_fma_f32 v[4:5], v[0:1], v[24:25], v[116:117]
	v_and_b32_sdwa v39, v24, v75 dst_sel:DWORD dst_unused:UNUSED_PAD src0_sel:WORD_1 src1_sel:DWORD
	v_add3_u32 v26, v26, v37, s13
	v_and_b32_e32 v7, 0xffff0000, v7
	v_and_b32_sdwa v34, v22, v75 dst_sel:DWORD dst_unused:UNUSED_PAD src0_sel:WORD_1 src1_sel:DWORD
	v_add3_u32 v25, v25, v40, s13
	global_store_dwordx2 v[16:17], v[28:29], off
	v_pk_fma_f32 v[16:17], v[0:1], v[22:23], v[86:87]
	v_or_b32_sdwa v33, v33, v21 dst_sel:DWORD dst_unused:UNUSED_PAD src0_sel:WORD_1 src1_sel:DWORD
	v_and_b32_e32 v21, 0xffff0000, v27
	v_add3_u32 v23, v23, v36, s13
	v_add3_u32 v35, v24, v39, s13
	v_mov_b32_e32 v6, v5
	v_or_b32_sdwa v24, v38, v7 dst_sel:DWORD dst_unused:UNUSED_PAD src0_sel:WORD_1 src1_sel:DWORD
	v_add3_u32 v22, v22, v34, s13
	v_and_b32_e32 v27, 0xffff0000, v25
	global_store_dwordx2 v[14:15], v[30:31], off
	v_mov_b32_e32 v5, v16
	v_mov_b32_e32 v7, v17
	v_or_b32_sdwa v25, v26, v21 dst_sel:DWORD dst_unused:UNUSED_PAD src0_sel:WORD_1 src1_sel:DWORD
	v_and_b32_e32 v15, 0xffff0000, v23
	v_or_b32_sdwa v14, v35, v27 dst_sel:DWORD dst_unused:UNUSED_PAD src0_sel:WORD_1 src1_sel:DWORD
	global_store_dwordx2 v[12:13], v[32:33], off
	v_or_b32_sdwa v15, v22, v15 dst_sel:DWORD dst_unused:UNUSED_PAD src0_sel:WORD_1 src1_sel:DWORD
	global_store_dwordx2 v[8:9], v[24:25], off
	global_store_dwordx2 v[10:11], v[14:15], off
	s_cbranch_scc0 .LBB0_637
; __device__ __forceinline__ float fexp(float x) { return __builtin_amdgcn_exp2f(1.4426950408889634f * x); }
; __device__ __forceinline__ unsigned pk2(float lo, float hi) { return f2bf(lo) | (f2bf(hi) << 16); }
; __device__ __forceinline__ void ret_scan_phase(const Params& p, int G) {
;     ...
;         {
;             const int e8 = t & 2047, sdh = t >> 11, dir = sdh & 1, h = (sdh >> 1) & 3, b = sdh >> 3, c0 = 256 + 16 * b;
;             const float Dk = fexp((dir ? p.in[11][h] : p.in[10][h]) * 128.0f);
;             float st[8] = {0.f, 0.f, 0.f, 0.f, 0.f, 0.f, 0.f, 0.f};
;             u32x4 v[16];
; #pragma unroll
;             for (int i = 0; i < 16; ++i) { const int c = dir ? (c0 + 15 - i) : (c0 + i); v[i] = *(const u32x4*)(kvbuf + ((size_t)(c * 4 + h) * 2 + dir) * 16384 + e8 * 8); }
; #pragma unroll
;             for (int i = 0; i < 16; ++i) { const int c = dir ? (c0 + 15 - i) : (c0 + i);
;                 u32x4 w; w.x = pk2(st[0], st[1]); w.y = pk2(st[2], st[3]); w.z = pk2(st[4], st[5]); w.w = pk2(st[6], st[7]); *(u32x4*)(kvbuf + ((size_t)(c * 4 + h) * 2 + dir) * 16384 + e8 * 8) = w;
;                 const unsigned vv[4] = {v[i].x, v[i].y, v[i].z, v[i].w};
; #pragma unroll
;                 for (int q = 0; q < 4; ++q) { st[2 * q] = st[2 * q] * Dk + bf2f((unsigned short)(vv[q] & 0xffffu)); st[2 * q + 1] = st[2 * q + 1] * Dk + bf2f((unsigned short)(vv[q] >> 16)); }
;             }
	v_bfe_u32 v2, v70, 11, 1
	v_mov_b32_e32 v0, s3
	v_mov_b32_e32 v1, s1
	v_cmp_eq_u32_e32 vcc, 0, v2
	v_bfe_u32 v76, v70, 12, 2
	v_mov_b32_e32 v3, s0
	v_cndmask_b32_e32 v1, v0, v1, vcc
	v_mov_b32_e32 v0, s2
	v_cndmask_b32_e32 v0, v0, v3, vcc
	v_lshlrev_b32_e32 v44, 2, v76
	v_lshl_add_u64 v[0:1], v[0:1], 0, v[44:45]
	global_load_dword v14, v[0:1], off nt
	v_ashrrev_i32_e32 v0, 10, v70
	v_and_b32_e32 v0, -16, v0
	v_add_u32_e32 v77, 0x100, v0
	v_add_u32_e32 v1, 0x10f, v0
	v_lshlrev_b32_e32 v44, 15, v2
	v_cndmask_b32_e32 v2, v1, v77, vcc
	v_lshlrev_b32_e32 v3, 4, v70
	v_add_u32_e32 v48, 0x10e, v0
	v_add_u32_e32 v49, 0x101, v0
	v_add_u32_e32 v50, 0x10d, v0
	v_add_u32_e32 v51, 0x102, v0
	v_add_u32_e32 v52, 0x10c, v0
	v_add_u32_e32 v53, 0x103, v0
	v_add_u32_e32 v15, 0x10b, v0
	v_add_u32_e32 v16, 0x104, v0
	v_add_u32_e32 v17, 0x10a, v0
	v_add_u32_e32 v18, 0x105, v0
	v_add_u32_e32 v19, 0x109, v0
	v_add_u32_e32 v20, 0x106, v0
	v_add_u32_e32 v4, 0x108, v0
	v_add_u32_e32 v0, 0x107, v0
	v_lshl_or_b32 v2, v2, 2, v76
	v_cndmask_b32_e32 v11, v4, v0, vcc
	v_cndmask_b32_e32 v21, v0, v4, vcc
	v_lshl_add_u64 v[0:1], s[8:9], 0, v[44:45]
	v_and_b32_e32 v44, 0x7ff0, v3
	v_ashrrev_i32_e32 v3, 31, v2
	v_lshl_add_u64 v[46:47], v[0:1], 0, v[44:45]
	v_lshlrev_b64 v[0:1], 16, v[2:3]
	v_lshl_add_u64 v[98:99], v[46:47], 0, v[0:1]
	global_load_dwordx4 v[82:85], v[98:99], off nt
	v_cndmask_b32_e32 v5, v48, v49, vcc
	v_cndmask_b32_e32 v6, v50, v51, vcc
	v_cndmask_b32_e32 v7, v52, v53, vcc
	v_cndmask_b32_e32 v8, v15, v16, vcc
	v_cndmask_b32_e32 v9, v17, v18, vcc
	v_cndmask_b32_e32 v10, v19, v20, vcc
	v_lshl_or_b32 v4, v5, 2, v76
	v_lshl_or_b32 v6, v6, 2, v76
	v_lshl_or_b32 v0, v7, 2, v76
	v_lshl_or_b32 v2, v8, 2, v76
	v_lshl_or_b32 v8, v9, 2, v76
	v_lshl_or_b32 v10, v10, 2, v76
	v_lshl_or_b32 v12, v11, 2, v76
	v_ashrrev_i32_e32 v5, 31, v4
	v_ashrrev_i32_e32 v7, 31, v6
	v_ashrrev_i32_e32 v1, 31, v0
	v_ashrrev_i32_e32 v3, 31, v2
	v_ashrrev_i32_e32 v9, 31, v8
	v_ashrrev_i32_e32 v11, 31, v10
	v_ashrrev_i32_e32 v13, 31, v12
	v_lshlrev_b64 v[4:5], 16, v[4:5]
	v_lshlrev_b64 v[6:7], 16, v[6:7]
	v_lshlrev_b64 v[0:1], 16, v[0:1]
	v_lshlrev_b64 v[2:3], 16, v[2:3]
	v_lshlrev_b64 v[8:9], 16, v[8:9]
	v_lshlrev_b64 v[10:11], 16, v[10:11]
	v_lshlrev_b64 v[12:13], 16, v[12:13]
	v_lshl_add_u64 v[100:101], v[46:47], 0, v[4:5]
	v_lshl_add_u64 v[102:103], v[46:47], 0, v[6:7]
	v_lshl_add_u64 v[104:105], v[46:47], 0, v[0:1]
	v_lshl_add_u64 v[68:69], v[46:47], 0, v[2:3]
	v_lshl_add_u64 v[66:67], v[46:47], 0, v[8:9]
	v_lshl_add_u64 v[64:65], v[46:47], 0, v[10:11]
	v_lshl_add_u64 v[62:63], v[46:47], 0, v[12:13]
	global_load_dwordx4 v[86:89], v[100:101], off nt
	global_load_dwordx4 v[90:93], v[102:103], off nt
	global_load_dwordx4 v[94:97], v[104:105], off nt
	global_load_dwordx4 v[40:43], v[68:69], off nt
	global_load_dwordx4 v[36:39], v[66:67], off nt
	global_load_dwordx4 v[32:35], v[64:65], off nt
	global_load_dwordx4 v[28:31], v[62:63], off nt
	v_add_u32_e32 v70, s12, v70
	s_waitcnt vmcnt(8)
	v_mul_f32_e32 v0, 0x43000000, v14
	v_mul_f32_e32 v2, 0x3fb8aa3b, v0
	v_lshl_or_b32 v0, v21, 2, v76
	v_ashrrev_i32_e32 v1, 31, v0
	v_lshlrev_b64 v[0:1], 16, v[0:1]
	v_lshl_add_u64 v[60:61], v[46:47], 0, v[0:1]
	v_cndmask_b32_e32 v0, v20, v19, vcc
	v_lshl_or_b32 v0, v0, 2, v76
	v_ashrrev_i32_e32 v1, 31, v0
	v_lshlrev_b64 v[0:1], 16, v[0:1]
	v_lshl_add_u64 v[58:59], v[46:47], 0, v[0:1]
	global_load_dwordx4 v[24:27], v[60:61], off nt
	global_load_dwordx4 v[20:23], v[58:59], off nt
	v_cndmask_b32_e32 v0, v18, v17, vcc
	v_lshl_or_b32 v0, v0, 2, v76
	v_ashrrev_i32_e32 v1, 31, v0
	v_lshlrev_b64 v[0:1], 16, v[0:1]
	v_lshl_add_u64 v[56:57], v[46:47], 0, v[0:1]
	v_cndmask_b32_e32 v0, v16, v15, vcc
	v_lshl_or_b32 v0, v0, 2, v76
	v_ashrrev_i32_e32 v1, 31, v0
	v_lshlrev_b64 v[0:1], 16, v[0:1]
	v_lshl_add_u64 v[54:55], v[46:47], 0, v[0:1]
	v_cndmask_b32_e32 v0, v53, v52, vcc
	v_lshl_or_b32 v0, v0, 2, v76
	global_load_dwordx4 v[16:19], v[56:57], off nt
	global_load_dwordx4 v[12:15], v[54:55], off nt
	v_ashrrev_i32_e32 v1, 31, v0
	v_lshlrev_b64 v[0:1], 16, v[0:1]
	v_lshl_add_u64 v[52:53], v[46:47], 0, v[0:1]
	v_cndmask_b32_e32 v0, v51, v50, vcc
	v_exp_f32_e32 v44, v2
	v_lshl_or_b32 v0, v0, 2, v76
	v_ashrrev_i32_e32 v1, 31, v0
	v_lshlrev_b64 v[0:1], 16, v[0:1]
	v_lshl_add_u64 v[50:51], v[46:47], 0, v[0:1]
	global_load_dwordx4 v[8:11], v[52:53], off nt
	global_load_dwordx4 v[4:7], v[50:51], off nt
	s_waitcnt vmcnt(13)
	v_lshlrev_b32_e32 v107, 16, v83
	global_store_dwordx4 v[98:99], v[78:81], off
	v_mul_f32_e32 v98, 0, v44
	v_lshlrev_b32_e32 v106, 16, v82
	v_and_b32_e32 v83, 0xffff0000, v83
	v_and_b32_e32 v82, 0xffff0000, v82
	v_pk_add_f32 v[108:109], v[98:99], v[82:83] op_sel_hi:[0,1]
	v_lshlrev_b32_e32 v83, 16, v85
	v_lshlrev_b32_e32 v82, 16, v84
	v_pk_add_f32 v[106:107], v[98:99], v[106:107] op_sel_hi:[0,1]
	v_pk_add_f32 v[110:111], v[98:99], v[82:83] op_sel_hi:[0,1]
	v_and_b32_e32 v83, 0xffff0000, v85
	v_and_b32_e32 v82, 0xffff0000, v84
	v_bfe_u32 v84, v109, 16, 1
	v_bfe_u32 v85, v108, 16, 1
	v_pk_add_f32 v[98:99], v[98:99], v[82:83] op_sel_hi:[0,1]
	v_add3_u32 v112, v108, v85, s13
	v_add3_u32 v113, v109, v84, s13
	v_bfe_u32 v84, v106, 16, 1
	v_bfe_u32 v85, v107, 16, 1
	v_bfe_u32 v114, v110, 16, 1
	v_bfe_u32 v115, v111, 16, 1
	v_bfe_u32 v82, v99, 16, 1
	v_bfe_u32 v83, v98, 16, 1
	v_add3_u32 v115, v111, v115, s13
	v_add3_u32 v114, v110, v114, s13
	v_add3_u32 v85, v107, v85, s13
	v_add3_u32 v84, v106, v84, s13
	v_add3_u32 v83, v98, v83, s13
	v_add3_u32 v82, v99, v82, s13
	v_lshrrev_b32_e32 v116, 16, v84
	v_lshrrev_b32_e32 v117, 16, v85
	v_lshrrev_b32_e32 v84, 16, v114
	v_lshrrev_b32_e32 v85, 16, v115
	v_and_or_b32 v85, v82, s14, v85
	v_and_or_b32 v84, v83, s14, v84
	v_and_or_b32 v83, v113, s14, v117
	v_and_or_b32 v82, v112, s14, v116
	global_store_dwordx4 v[100:101], v[82:85], off
	v_cndmask_b32_e32 v0, v49, v48, vcc
	v_lshl_or_b32 v0, v0, 2, v76
	s_waitcnt vmcnt(14)
; __device__ __forceinline__ unsigned pk2(float lo, float hi) { return f2bf(lo) | (f2bf(hi) << 16); }
; __device__ __forceinline__ void ret_scan_phase(const Params& p, int G) {
;     ...
;             for (int i = 0; i < 16; ++i) { const int c = dir ? (c0 + 15 - i) : (c0 + i); v[i] = *(const u32x4*)(kvbuf + ((size_t)(c * 4 + h) * 2 + dir) * 16384 + e8 * 8); }
; #pragma unroll
;             for (int i = 0; i < 16; ++i) { const int c = dir ? (c0 + 15 - i) : (c0 + i);
;                 u32x4 w; w.x = pk2(st[0], st[1]); w.y = pk2(st[2], st[3]); w.z = pk2(st[4], st[5]); w.w = pk2(st[6], st[7]); *(u32x4*)(kvbuf + ((size_t)(c * 4 + h) * 2 + dir) * 16384 + e8 * 8) = w;
;                 const unsigned vv[4] = {v[i].x, v[i].y, v[i].z, v[i].w};
; #pragma unroll
;                 for (int q = 0; q < 4; ++q) { st[2 * q] = st[2 * q] * Dk + bf2f((unsigned short)(vv[q] & 0xffffu)); st[2 * q + 1] = st[2 * q + 1] * Dk + bf2f((unsigned short)(vv[q] >> 16)); }
	v_lshlrev_b32_e32 v83, 16, v87
	v_lshlrev_b32_e32 v82, 16, v86
	v_pk_fma_f32 v[100:101], v[44:45], v[106:107], v[82:83] op_sel_hi:[0,1,1]
	v_and_b32_e32 v83, 0xffff0000, v87
	v_and_b32_e32 v82, 0xffff0000, v86
	v_pk_fma_f32 v[86:87], v[44:45], v[108:109], v[82:83] op_sel_hi:[0,1,1]
	v_lshlrev_b32_e32 v83, 16, v89
	v_lshlrev_b32_e32 v82, 16, v88
	v_pk_fma_f32 v[106:107], v[44:45], v[110:111], v[82:83] op_sel_hi:[0,1,1]
	v_and_b32_e32 v83, 0xffff0000, v89
	v_and_b32_e32 v82, 0xffff0000, v88
	v_bfe_u32 v84, v87, 16, 1
	v_bfe_u32 v85, v86, 16, 1
	v_pk_fma_f32 v[88:89], v[44:45], v[98:99], v[82:83] op_sel_hi:[0,1,1]
	v_add3_u32 v98, v86, v85, s13
	v_add3_u32 v99, v87, v84, s13
	v_bfe_u32 v84, v100, 16, 1
	v_bfe_u32 v85, v101, 16, 1
	v_bfe_u32 v108, v106, 16, 1
	v_bfe_u32 v109, v107, 16, 1
	v_bfe_u32 v82, v89, 16, 1
	v_bfe_u32 v83, v88, 16, 1
	v_add3_u32 v109, v107, v109, s13
	v_add3_u32 v108, v106, v108, s13
	v_add3_u32 v85, v101, v85, s13
	v_add3_u32 v84, v100, v84, s13
	v_add3_u32 v83, v88, v83, s13
	v_add3_u32 v82, v89, v82, s13
	v_lshrrev_b32_e32 v110, 16, v84
	v_lshrrev_b32_e32 v111, 16, v85
	v_lshrrev_b32_e32 v84, 16, v108
	v_lshrrev_b32_e32 v85, 16, v109
	v_and_or_b32 v85, v82, s14, v85
	v_and_or_b32 v84, v83, s14, v84
	v_and_or_b32 v83, v99, s14, v111
	v_and_or_b32 v82, v98, s14, v110
	global_store_dwordx4 v[102:103], v[82:85], off
	v_ashrrev_i32_e32 v1, 31, v0
	v_lshlrev_b64 v[0:1], 16, v[0:1]
	s_waitcnt vmcnt(14)
	v_lshlrev_b32_e32 v83, 16, v91
	v_lshlrev_b32_e32 v82, 16, v90
	v_pk_fma_f32 v[98:99], v[44:45], v[100:101], v[82:83] op_sel_hi:[0,1,1]
	v_and_b32_e32 v83, 0xffff0000, v91
	v_and_b32_e32 v82, 0xffff0000, v90
	v_pk_fma_f32 v[86:87], v[44:45], v[86:87], v[82:83] op_sel_hi:[0,1,1]
	v_lshlrev_b32_e32 v83, 16, v93
	v_lshlrev_b32_e32 v82, 16, v92
	v_pk_fma_f32 v[90:91], v[44:45], v[106:107], v[82:83] op_sel_hi:[0,1,1]
	v_and_b32_e32 v83, 0xffff0000, v93
	v_and_b32_e32 v82, 0xffff0000, v92
	v_bfe_u32 v84, v87, 16, 1
	v_bfe_u32 v85, v86, 16, 1
	v_pk_fma_f32 v[88:89], v[44:45], v[88:89], v[82:83] op_sel_hi:[0,1,1]
	v_add3_u32 v92, v86, v85, s13
	v_add3_u32 v93, v87, v84, s13
	v_bfe_u32 v84, v98, 16, 1
	v_bfe_u32 v85, v99, 16, 1
	v_bfe_u32 v100, v90, 16, 1
	v_bfe_u32 v101, v91, 16, 1
	v_lshl_add_u64 v[48:49], v[46:47], 0, v[0:1]
	v_bfe_u32 v82, v89, 16, 1
	v_bfe_u32 v83, v88, 16, 1
	v_add3_u32 v101, v91, v101, s13
	v_add3_u32 v100, v90, v100, s13
	v_add3_u32 v85, v99, v85, s13
	v_add3_u32 v84, v98, v84, s13
	global_load_dwordx4 v[0:3], v[48:49], off nt
	v_add3_u32 v83, v88, v83, s13
	v_add3_u32 v82, v89, v82, s13
	v_lshrrev_b32_e32 v102, 16, v84
	v_lshrrev_b32_e32 v103, 16, v85
	v_lshrrev_b32_e32 v84, 16, v100
	v_lshrrev_b32_e32 v85, 16, v101
	v_and_or_b32 v85, v82, s14, v85
	v_and_or_b32 v84, v83, s14, v84
	v_and_or_b32 v83, v93, s14, v103
	v_and_or_b32 v82, v92, s14, v102
	global_store_dwordx4 v[104:105], v[82:85], off
	s_waitcnt vmcnt(15)
	s_nop 0
	v_lshlrev_b32_e32 v83, 16, v95
	v_lshlrev_b32_e32 v82, 16, v94
	v_pk_fma_f32 v[92:93], v[44:45], v[98:99], v[82:83] op_sel_hi:[0,1,1]
	v_and_b32_e32 v83, 0xffff0000, v95
	v_and_b32_e32 v82, 0xffff0000, v94
	v_pk_fma_f32 v[86:87], v[44:45], v[86:87], v[82:83] op_sel_hi:[0,1,1]
	v_lshlrev_b32_e32 v83, 16, v97
	v_lshlrev_b32_e32 v82, 16, v96
	v_pk_fma_f32 v[90:91], v[44:45], v[90:91], v[82:83] op_sel_hi:[0,1,1]
	v_and_b32_e32 v83, 0xffff0000, v97
	v_and_b32_e32 v82, 0xffff0000, v96
	v_bfe_u32 v84, v87, 16, 1
	v_bfe_u32 v85, v86, 16, 1
	v_pk_fma_f32 v[88:89], v[44:45], v[88:89], v[82:83] op_sel_hi:[0,1,1]
	v_add3_u32 v94, v86, v85, s13
	v_add3_u32 v95, v87, v84, s13
	v_bfe_u32 v84, v92, 16, 1
	v_bfe_u32 v85, v93, 16, 1
	v_bfe_u32 v96, v90, 16, 1
	v_bfe_u32 v97, v91, 16, 1
	v_bfe_u32 v82, v89, 16, 1
	v_bfe_u32 v83, v88, 16, 1
	v_add3_u32 v97, v91, v97, s13
	v_add3_u32 v96, v90, v96, s13
	v_add3_u32 v85, v93, v85, s13
	v_add3_u32 v84, v92, v84, s13
	v_add3_u32 v83, v88, v83, s13
	v_add3_u32 v82, v89, v82, s13
	v_lshrrev_b32_e32 v98, 16, v84
	v_lshrrev_b32_e32 v99, 16, v85
	v_lshrrev_b32_e32 v84, 16, v96
	v_lshrrev_b32_e32 v85, 16, v97
	v_and_or_b32 v85, v82, s14, v85
	v_and_or_b32 v84, v83, s14, v84
	v_and_or_b32 v83, v95, s14, v99
	v_and_or_b32 v82, v94, s14, v98
	global_store_dwordx4 v[68:69], v[82:85], off
	s_waitcnt vmcnt(15)
	v_lshlrev_b32_e32 v69, 16, v41
	v_lshlrev_b32_e32 v68, 16, v40
	v_and_b32_e32 v41, 0xffff0000, v41
	v_and_b32_e32 v40, 0xffff0000, v40
	v_pk_fma_f32 v[82:83], v[44:45], v[86:87], v[40:41] op_sel_hi:[0,1,1]
	v_lshlrev_b32_e32 v41, 16, v43
	v_lshlrev_b32_e32 v40, 16, v42
	v_pk_fma_f32 v[68:69], v[44:45], v[92:93], v[68:69] op_sel_hi:[0,1,1]
	v_pk_fma_f32 v[84:85], v[44:45], v[90:91], v[40:41] op_sel_hi:[0,1,1]
	v_and_b32_e32 v41, 0xffff0000, v43
	v_and_b32_e32 v40, 0xffff0000, v42
	v_bfe_u32 v42, v83, 16, 1
	v_bfe_u32 v43, v82, 16, 1
	v_pk_fma_f32 v[86:87], v[44:45], v[88:89], v[40:41] op_sel_hi:[0,1,1]
	v_add3_u32 v88, v82, v43, s13
	v_add3_u32 v89, v83, v42, s13
	v_bfe_u32 v42, v68, 16, 1
	v_bfe_u32 v43, v69, 16, 1
	v_bfe_u32 v90, v84, 16, 1
	v_bfe_u32 v91, v85, 16, 1
	v_bfe_u32 v40, v87, 16, 1
	v_bfe_u32 v41, v86, 16, 1
	v_add3_u32 v91, v85, v91, s13
	v_add3_u32 v90, v84, v90, s13
	v_add3_u32 v43, v69, v43, s13
	v_add3_u32 v42, v68, v42, s13
	v_add3_u32 v41, v86, v41, s13
	v_add3_u32 v40, v87, v40, s13
	v_lshrrev_b32_e32 v92, 16, v42
	v_lshrrev_b32_e32 v93, 16, v43
	v_lshrrev_b32_e32 v42, 16, v90
	v_lshrrev_b32_e32 v43, 16, v91
	v_and_or_b32 v43, v40, s14, v43
	v_and_or_b32 v42, v41, s14, v42
	v_and_or_b32 v41, v89, s14, v93
	v_and_or_b32 v40, v88, s14, v92
	global_store_dwordx4 v[66:67], v[40:43], off
	s_waitcnt vmcnt(15)
; __device__ __forceinline__ unsigned pk2(float lo, float hi) { return f2bf(lo) | (f2bf(hi) << 16); }
; __device__ __forceinline__ void ret_scan_phase(const Params& p, int G) {
;     ...
;             for (int i = 0; i < 16; ++i) { const int c = dir ? (c0 + 15 - i) : (c0 + i);
;                 u32x4 w; w.x = pk2(st[0], st[1]); w.y = pk2(st[2], st[3]); w.z = pk2(st[4], st[5]); w.w = pk2(st[6], st[7]); *(u32x4*)(kvbuf + ((size_t)(c * 4 + h) * 2 + dir) * 16384 + e8 * 8) = w;
;                 const unsigned vv[4] = {v[i].x, v[i].y, v[i].z, v[i].w};
; #pragma unroll
;                 for (int q = 0; q < 4; ++q) { st[2 * q] = st[2 * q] * Dk + bf2f((unsigned short)(vv[q] & 0xffffu)); st[2 * q + 1] = st[2 * q + 1] * Dk + bf2f((unsigned short)(vv[q] >> 16)); }
	s_nop 0
	v_lshlrev_b32_e32 v41, 16, v37
	v_lshlrev_b32_e32 v40, 16, v36
	v_and_b32_e32 v37, 0xffff0000, v37
	v_and_b32_e32 v36, 0xffff0000, v36
	v_pk_fma_f32 v[42:43], v[44:45], v[82:83], v[36:37] op_sel_hi:[0,1,1]
	v_lshlrev_b32_e32 v37, 16, v39
	v_lshlrev_b32_e32 v36, 16, v38
	v_pk_fma_f32 v[40:41], v[44:45], v[68:69], v[40:41] op_sel_hi:[0,1,1]
	v_pk_fma_f32 v[66:67], v[44:45], v[84:85], v[36:37] op_sel_hi:[0,1,1]
	v_and_b32_e32 v37, 0xffff0000, v39
	v_and_b32_e32 v36, 0xffff0000, v38
	v_bfe_u32 v38, v43, 16, 1
	v_bfe_u32 v39, v42, 16, 1
	v_pk_fma_f32 v[68:69], v[44:45], v[86:87], v[36:37] op_sel_hi:[0,1,1]
	v_add3_u32 v82, v42, v39, s13
	v_add3_u32 v83, v43, v38, s13
	v_bfe_u32 v38, v40, 16, 1
	v_bfe_u32 v39, v41, 16, 1
	v_bfe_u32 v84, v66, 16, 1
	v_bfe_u32 v85, v67, 16, 1
	v_bfe_u32 v36, v69, 16, 1
	v_bfe_u32 v37, v68, 16, 1
	v_add3_u32 v85, v67, v85, s13
	v_add3_u32 v84, v66, v84, s13
	v_add3_u32 v39, v41, v39, s13
	v_add3_u32 v38, v40, v38, s13
	v_add3_u32 v37, v68, v37, s13
	v_add3_u32 v36, v69, v36, s13
	v_lshrrev_b32_e32 v86, 16, v38
	v_lshrrev_b32_e32 v87, 16, v39
	v_lshrrev_b32_e32 v38, 16, v84
	v_lshrrev_b32_e32 v39, 16, v85
	v_and_or_b32 v39, v36, s14, v39
	v_and_or_b32 v38, v37, s14, v38
	v_and_or_b32 v37, v83, s14, v87
	v_and_or_b32 v36, v82, s14, v86
	global_store_dwordx4 v[64:65], v[36:39], off
	s_waitcnt vmcnt(15)
	s_nop 0
	v_lshlrev_b32_e32 v37, 16, v33
	v_lshlrev_b32_e32 v36, 16, v32
	v_and_b32_e32 v33, 0xffff0000, v33
	v_and_b32_e32 v32, 0xffff0000, v32
	v_pk_fma_f32 v[38:39], v[44:45], v[42:43], v[32:33] op_sel_hi:[0,1,1]
	v_lshlrev_b32_e32 v33, 16, v35
	v_lshlrev_b32_e32 v32, 16, v34
	v_pk_fma_f32 v[36:37], v[44:45], v[40:41], v[36:37] op_sel_hi:[0,1,1]
	v_pk_fma_f32 v[40:41], v[44:45], v[66:67], v[32:33] op_sel_hi:[0,1,1]
	v_and_b32_e32 v33, 0xffff0000, v35
	v_and_b32_e32 v32, 0xffff0000, v34
	v_bfe_u32 v34, v39, 16, 1
	v_bfe_u32 v35, v38, 16, 1
	v_pk_fma_f32 v[42:43], v[44:45], v[68:69], v[32:33] op_sel_hi:[0,1,1]
	v_add3_u32 v64, v38, v35, s13
	v_add3_u32 v65, v39, v34, s13
	v_bfe_u32 v34, v36, 16, 1
	v_bfe_u32 v35, v37, 16, 1
	v_bfe_u32 v66, v40, 16, 1
	v_bfe_u32 v67, v41, 16, 1
	v_bfe_u32 v32, v43, 16, 1
	v_bfe_u32 v33, v42, 16, 1
	v_add3_u32 v67, v41, v67, s13
	v_add3_u32 v66, v40, v66, s13
	v_add3_u32 v35, v37, v35, s13
	v_add3_u32 v34, v36, v34, s13
	v_add3_u32 v33, v42, v33, s13
	v_add3_u32 v32, v43, v32, s13
	v_lshrrev_b32_e32 v68, 16, v34
	v_lshrrev_b32_e32 v69, 16, v35
	v_lshrrev_b32_e32 v34, 16, v66
	v_lshrrev_b32_e32 v35, 16, v67
	v_and_or_b32 v35, v32, s14, v35
	v_and_or_b32 v34, v33, s14, v34
	v_and_or_b32 v33, v65, s14, v69
	v_and_or_b32 v32, v64, s14, v68
	global_store_dwordx4 v[62:63], v[32:35], off
	s_waitcnt vmcnt(15)
	s_nop 0
	v_lshlrev_b32_e32 v33, 16, v29
	v_lshlrev_b32_e32 v32, 16, v28
	v_and_b32_e32 v29, 0xffff0000, v29
	v_and_b32_e32 v28, 0xffff0000, v28
	v_pk_fma_f32 v[34:35], v[44:45], v[38:39], v[28:29] op_sel_hi:[0,1,1]
	v_lshlrev_b32_e32 v29, 16, v31
	v_lshlrev_b32_e32 v28, 16, v30
	v_pk_fma_f32 v[32:33], v[44:45], v[36:37], v[32:33] op_sel_hi:[0,1,1]
	v_pk_fma_f32 v[36:37], v[44:45], v[40:41], v[28:29] op_sel_hi:[0,1,1]
	v_and_b32_e32 v29, 0xffff0000, v31
	v_and_b32_e32 v28, 0xffff0000, v30
	v_bfe_u32 v30, v35, 16, 1
	v_bfe_u32 v31, v34, 16, 1
	v_pk_fma_f32 v[38:39], v[44:45], v[42:43], v[28:29] op_sel_hi:[0,1,1]
	v_add3_u32 v40, v34, v31, s13
	v_add3_u32 v41, v35, v30, s13
	v_bfe_u32 v30, v32, 16, 1
	v_bfe_u32 v31, v33, 16, 1
	v_bfe_u32 v42, v36, 16, 1
	v_bfe_u32 v43, v37, 16, 1
	v_bfe_u32 v28, v39, 16, 1
	v_bfe_u32 v29, v38, 16, 1
	v_add3_u32 v43, v37, v43, s13
	v_add3_u32 v42, v36, v42, s13
	v_add3_u32 v31, v33, v31, s13
	v_add3_u32 v30, v32, v30, s13
	v_add3_u32 v29, v38, v29, s13
	v_add3_u32 v28, v39, v28, s13
	v_lshrrev_b32_e32 v62, 16, v30
	v_lshrrev_b32_e32 v63, 16, v31
	v_lshrrev_b32_e32 v30, 16, v42
	v_lshrrev_b32_e32 v31, 16, v43
	v_and_or_b32 v31, v28, s14, v31
	v_and_or_b32 v30, v29, s14, v30
	v_and_or_b32 v29, v41, s14, v63
	v_and_or_b32 v28, v40, s14, v62
	global_store_dwordx4 v[60:61], v[28:31], off
	s_waitcnt vmcnt(15)
	s_nop 0
	v_lshlrev_b32_e32 v29, 16, v25
	v_lshlrev_b32_e32 v28, 16, v24
	v_and_b32_e32 v25, 0xffff0000, v25
	v_and_b32_e32 v24, 0xffff0000, v24
	v_pk_fma_f32 v[30:31], v[44:45], v[34:35], v[24:25] op_sel_hi:[0,1,1]
	v_lshlrev_b32_e32 v25, 16, v27
	v_lshlrev_b32_e32 v24, 16, v26
	v_pk_fma_f32 v[28:29], v[44:45], v[32:33], v[28:29] op_sel_hi:[0,1,1]
	v_pk_fma_f32 v[32:33], v[44:45], v[36:37], v[24:25] op_sel_hi:[0,1,1]
	v_and_b32_e32 v25, 0xffff0000, v27
	v_and_b32_e32 v24, 0xffff0000, v26
	v_bfe_u32 v26, v31, 16, 1
	v_bfe_u32 v27, v30, 16, 1
	v_pk_fma_f32 v[34:35], v[44:45], v[38:39], v[24:25] op_sel_hi:[0,1,1]
	v_add3_u32 v36, v30, v27, s13
	v_add3_u32 v37, v31, v26, s13
	v_bfe_u32 v26, v28, 16, 1
	v_bfe_u32 v27, v29, 16, 1
	v_bfe_u32 v38, v32, 16, 1
	v_bfe_u32 v39, v33, 16, 1
	v_bfe_u32 v24, v35, 16, 1
	v_bfe_u32 v25, v34, 16, 1
	v_add3_u32 v39, v33, v39, s13
	v_add3_u32 v38, v32, v38, s13
	v_add3_u32 v27, v29, v27, s13
	v_add3_u32 v26, v28, v26, s13
	v_add3_u32 v25, v34, v25, s13
	v_add3_u32 v24, v35, v24, s13
	v_lshrrev_b32_e32 v40, 16, v26
	v_lshrrev_b32_e32 v41, 16, v27
	v_lshrrev_b32_e32 v26, 16, v38
	v_lshrrev_b32_e32 v27, 16, v39
	v_and_or_b32 v27, v24, s14, v27
	v_and_or_b32 v26, v25, s14, v26
	v_and_or_b32 v25, v37, s14, v41
	v_and_or_b32 v24, v36, s14, v40
	global_store_dwordx4 v[58:59], v[24:27], off
	s_waitcnt vmcnt(15)
; __device__ __forceinline__ unsigned pk2(float lo, float hi) { return f2bf(lo) | (f2bf(hi) << 16); }
; __device__ __forceinline__ void ret_scan_phase(const Params& p, int G) {
;     ...
;             for (int i = 0; i < 16; ++i) { const int c = dir ? (c0 + 15 - i) : (c0 + i);
;                 u32x4 w; w.x = pk2(st[0], st[1]); w.y = pk2(st[2], st[3]); w.z = pk2(st[4], st[5]); w.w = pk2(st[6], st[7]); *(u32x4*)(kvbuf + ((size_t)(c * 4 + h) * 2 + dir) * 16384 + e8 * 8) = w;
;                 const unsigned vv[4] = {v[i].x, v[i].y, v[i].z, v[i].w};
; #pragma unroll
;                 for (int q = 0; q < 4; ++q) { st[2 * q] = st[2 * q] * Dk + bf2f((unsigned short)(vv[q] & 0xffffu)); st[2 * q + 1] = st[2 * q + 1] * Dk + bf2f((unsigned short)(vv[q] >> 16)); }
	s_nop 0
	v_lshlrev_b32_e32 v25, 16, v21
	v_lshlrev_b32_e32 v24, 16, v20
	v_and_b32_e32 v21, 0xffff0000, v21
	v_and_b32_e32 v20, 0xffff0000, v20
	v_pk_fma_f32 v[26:27], v[44:45], v[30:31], v[20:21] op_sel_hi:[0,1,1]
	v_lshlrev_b32_e32 v21, 16, v23
	v_lshlrev_b32_e32 v20, 16, v22
	v_pk_fma_f32 v[24:25], v[44:45], v[28:29], v[24:25] op_sel_hi:[0,1,1]
	v_pk_fma_f32 v[28:29], v[44:45], v[32:33], v[20:21] op_sel_hi:[0,1,1]
	v_and_b32_e32 v21, 0xffff0000, v23
	v_and_b32_e32 v20, 0xffff0000, v22
	v_bfe_u32 v22, v27, 16, 1
	v_bfe_u32 v23, v26, 16, 1
	v_pk_fma_f32 v[30:31], v[44:45], v[34:35], v[20:21] op_sel_hi:[0,1,1]
	v_add3_u32 v32, v26, v23, s13
	v_add3_u32 v33, v27, v22, s13
	v_bfe_u32 v22, v24, 16, 1
	v_bfe_u32 v23, v25, 16, 1
	v_bfe_u32 v34, v28, 16, 1
	v_bfe_u32 v35, v29, 16, 1
	v_bfe_u32 v20, v31, 16, 1
	v_bfe_u32 v21, v30, 16, 1
	v_add3_u32 v35, v29, v35, s13
	v_add3_u32 v34, v28, v34, s13
	v_add3_u32 v23, v25, v23, s13
	v_add3_u32 v22, v24, v22, s13
	v_add3_u32 v21, v30, v21, s13
	v_add3_u32 v20, v31, v20, s13
	v_lshrrev_b32_e32 v36, 16, v22
	v_lshrrev_b32_e32 v37, 16, v23
	v_lshrrev_b32_e32 v22, 16, v34
	v_lshrrev_b32_e32 v23, 16, v35
	v_and_or_b32 v23, v20, s14, v23
	v_and_or_b32 v22, v21, s14, v22
	v_and_or_b32 v21, v33, s14, v37
	v_and_or_b32 v20, v32, s14, v36
	global_store_dwordx4 v[56:57], v[20:23], off
	s_waitcnt vmcnt(15)
	s_nop 0
	v_lshlrev_b32_e32 v21, 16, v17
	v_lshlrev_b32_e32 v20, 16, v16
	v_and_b32_e32 v17, 0xffff0000, v17
	v_and_b32_e32 v16, 0xffff0000, v16
	v_pk_fma_f32 v[22:23], v[44:45], v[26:27], v[16:17] op_sel_hi:[0,1,1]
	v_lshlrev_b32_e32 v17, 16, v19
	v_lshlrev_b32_e32 v16, 16, v18
	v_pk_fma_f32 v[20:21], v[44:45], v[24:25], v[20:21] op_sel_hi:[0,1,1]
	v_pk_fma_f32 v[24:25], v[44:45], v[28:29], v[16:17] op_sel_hi:[0,1,1]
	v_and_b32_e32 v17, 0xffff0000, v19
	v_and_b32_e32 v16, 0xffff0000, v18
	v_bfe_u32 v18, v23, 16, 1
	v_bfe_u32 v19, v22, 16, 1
	v_pk_fma_f32 v[26:27], v[44:45], v[30:31], v[16:17] op_sel_hi:[0,1,1]
	v_add3_u32 v28, v22, v19, s13
	v_add3_u32 v29, v23, v18, s13
	v_bfe_u32 v18, v20, 16, 1
	v_bfe_u32 v19, v21, 16, 1
	v_bfe_u32 v30, v24, 16, 1
	v_bfe_u32 v31, v25, 16, 1
	v_bfe_u32 v16, v27, 16, 1
	v_bfe_u32 v17, v26, 16, 1
	v_add3_u32 v31, v25, v31, s13
	v_add3_u32 v30, v24, v30, s13
	v_add3_u32 v19, v21, v19, s13
	v_add3_u32 v18, v20, v18, s13
	v_add3_u32 v17, v26, v17, s13
	v_add3_u32 v16, v27, v16, s13
	v_lshrrev_b32_e32 v32, 16, v18
	v_lshrrev_b32_e32 v33, 16, v19
	v_lshrrev_b32_e32 v18, 16, v30
	v_lshrrev_b32_e32 v19, 16, v31
	v_and_or_b32 v19, v16, s14, v19
	v_and_or_b32 v18, v17, s14, v18
	v_and_or_b32 v17, v29, s14, v33
	v_and_or_b32 v16, v28, s14, v32
	global_store_dwordx4 v[54:55], v[16:19], off
	s_waitcnt vmcnt(15)
	s_nop 0
	v_lshlrev_b32_e32 v17, 16, v13
	v_lshlrev_b32_e32 v16, 16, v12
	v_and_b32_e32 v13, 0xffff0000, v13
	v_and_b32_e32 v12, 0xffff0000, v12
	v_pk_fma_f32 v[18:19], v[44:45], v[22:23], v[12:13] op_sel_hi:[0,1,1]
	v_lshlrev_b32_e32 v13, 16, v15
	v_lshlrev_b32_e32 v12, 16, v14
	v_pk_fma_f32 v[16:17], v[44:45], v[20:21], v[16:17] op_sel_hi:[0,1,1]
	v_pk_fma_f32 v[20:21], v[44:45], v[24:25], v[12:13] op_sel_hi:[0,1,1]
	v_and_b32_e32 v13, 0xffff0000, v15
	v_and_b32_e32 v12, 0xffff0000, v14
	v_bfe_u32 v14, v19, 16, 1
	v_bfe_u32 v15, v18, 16, 1
	v_pk_fma_f32 v[22:23], v[44:45], v[26:27], v[12:13] op_sel_hi:[0,1,1]
	v_add3_u32 v24, v18, v15, s13
	v_add3_u32 v25, v19, v14, s13
	v_bfe_u32 v14, v16, 16, 1
	v_bfe_u32 v15, v17, 16, 1
	v_bfe_u32 v26, v20, 16, 1
	v_bfe_u32 v27, v21, 16, 1
	v_bfe_u32 v12, v23, 16, 1
	v_bfe_u32 v13, v22, 16, 1
	v_add3_u32 v27, v21, v27, s13
	v_add3_u32 v26, v20, v26, s13
	v_add3_u32 v15, v17, v15, s13
	v_add3_u32 v14, v16, v14, s13
	v_add3_u32 v13, v22, v13, s13
	v_add3_u32 v12, v23, v12, s13
	v_lshrrev_b32_e32 v28, 16, v14
	v_lshrrev_b32_e32 v29, 16, v15
	v_lshrrev_b32_e32 v14, 16, v26
	v_lshrrev_b32_e32 v15, 16, v27
	v_and_or_b32 v15, v12, s14, v15
	v_and_or_b32 v14, v13, s14, v14
	v_and_or_b32 v13, v25, s14, v29
	v_and_or_b32 v12, v24, s14, v28
	global_store_dwordx4 v[52:53], v[12:15], off
	s_waitcnt vmcnt(15)
; __device__ __forceinline__ unsigned pk2(float lo, float hi) { return f2bf(lo) | (f2bf(hi) << 16); }
; __device__ __forceinline__ void ret_scan_phase(const Params& p, int G) {
;     ...
;     for (int t = blockIdx.x * NTHR + threadIdx.x; t < 131072; t += nthr) {
;     ...
;             for (int i = 0; i < 16; ++i) { const int c = dir ? (c0 + 15 - i) : (c0 + i);
;                 u32x4 w; w.x = pk2(st[0], st[1]); w.y = pk2(st[2], st[3]); w.z = pk2(st[4], st[5]); w.w = pk2(st[6], st[7]); *(u32x4*)(kvbuf + ((size_t)(c * 4 + h) * 2 + dir) * 16384 + e8 * 8) = w;
;                 const unsigned vv[4] = {v[i].x, v[i].y, v[i].z, v[i].w};
; #pragma unroll
;                 for (int q = 0; q < 4; ++q) { st[2 * q] = st[2 * q] * Dk + bf2f((unsigned short)(vv[q] & 0xffffu)); st[2 * q + 1] = st[2 * q + 1] * Dk + bf2f((unsigned short)(vv[q] >> 16)); }
	s_nop 0
	v_lshlrev_b32_e32 v13, 16, v9
	v_lshlrev_b32_e32 v12, 16, v8
	v_and_b32_e32 v9, 0xffff0000, v9
	v_and_b32_e32 v8, 0xffff0000, v8
	v_pk_fma_f32 v[14:15], v[44:45], v[18:19], v[8:9] op_sel_hi:[0,1,1]
	v_lshlrev_b32_e32 v9, 16, v11
	v_lshlrev_b32_e32 v8, 16, v10
	v_pk_fma_f32 v[12:13], v[44:45], v[16:17], v[12:13] op_sel_hi:[0,1,1]
	v_pk_fma_f32 v[16:17], v[44:45], v[20:21], v[8:9] op_sel_hi:[0,1,1]
	v_and_b32_e32 v9, 0xffff0000, v11
	v_and_b32_e32 v8, 0xffff0000, v10
	v_bfe_u32 v10, v15, 16, 1
	v_bfe_u32 v11, v14, 16, 1
	v_pk_fma_f32 v[18:19], v[44:45], v[22:23], v[8:9] op_sel_hi:[0,1,1]
	v_add3_u32 v20, v14, v11, s13
	v_add3_u32 v21, v15, v10, s13
	v_bfe_u32 v10, v12, 16, 1
	v_bfe_u32 v11, v13, 16, 1
	v_bfe_u32 v22, v16, 16, 1
	v_bfe_u32 v23, v17, 16, 1
	v_bfe_u32 v8, v19, 16, 1
	v_bfe_u32 v9, v18, 16, 1
	v_add3_u32 v23, v17, v23, s13
	v_add3_u32 v22, v16, v22, s13
	v_add3_u32 v11, v13, v11, s13
	v_add3_u32 v10, v12, v10, s13
	v_add3_u32 v9, v18, v9, s13
	v_add3_u32 v8, v19, v8, s13
	v_lshrrev_b32_e32 v24, 16, v10
	v_lshrrev_b32_e32 v25, 16, v11
	v_lshrrev_b32_e32 v10, 16, v22
	v_lshrrev_b32_e32 v11, 16, v23
	v_and_or_b32 v11, v8, s14, v11
	v_and_or_b32 v10, v9, s14, v10
	v_and_or_b32 v9, v21, s14, v25
	v_and_or_b32 v8, v20, s14, v24
	global_store_dwordx4 v[50:51], v[8:11], off
	s_waitcnt vmcnt(15)
	s_nop 0
	v_lshlrev_b32_e32 v9, 16, v5
	v_lshlrev_b32_e32 v8, 16, v4
	v_and_b32_e32 v5, 0xffff0000, v5
	v_and_b32_e32 v4, 0xffff0000, v4
	v_pk_fma_f32 v[10:11], v[44:45], v[14:15], v[4:5] op_sel_hi:[0,1,1]
	v_lshlrev_b32_e32 v5, 16, v7
	v_lshlrev_b32_e32 v4, 16, v6
	v_pk_fma_f32 v[8:9], v[44:45], v[12:13], v[8:9] op_sel_hi:[0,1,1]
	v_pk_fma_f32 v[12:13], v[44:45], v[16:17], v[4:5] op_sel_hi:[0,1,1]
	v_and_b32_e32 v5, 0xffff0000, v7
	v_and_b32_e32 v4, 0xffff0000, v6
	v_bfe_u32 v6, v11, 16, 1
	v_bfe_u32 v7, v10, 16, 1
	v_pk_fma_f32 v[14:15], v[44:45], v[18:19], v[4:5] op_sel_hi:[0,1,1]
	v_add3_u32 v16, v10, v7, s13
	v_add3_u32 v17, v11, v6, s13
	v_bfe_u32 v6, v8, 16, 1
	v_bfe_u32 v7, v9, 16, 1
	v_bfe_u32 v18, v12, 16, 1
	v_bfe_u32 v19, v13, 16, 1
	v_bfe_u32 v4, v15, 16, 1
	v_bfe_u32 v5, v14, 16, 1
	v_add3_u32 v19, v13, v19, s13
	v_add3_u32 v18, v12, v18, s13
	v_add3_u32 v7, v9, v7, s13
	v_add3_u32 v6, v8, v6, s13
	v_add3_u32 v5, v14, v5, s13
	v_add3_u32 v4, v15, v4, s13
	v_lshrrev_b32_e32 v20, 16, v6
	v_lshrrev_b32_e32 v21, 16, v7
	v_lshrrev_b32_e32 v6, 16, v18
	v_lshrrev_b32_e32 v7, 16, v19
	v_and_or_b32 v7, v4, s14, v7
	v_and_or_b32 v6, v5, s14, v6
	v_and_or_b32 v5, v17, s14, v21
	v_and_or_b32 v4, v16, s14, v20
	global_store_dwordx4 v[48:49], v[4:7], off
	s_waitcnt vmcnt(12)
	s_nop 0
	v_lshlrev_b32_e32 v7, 16, v3
	v_lshlrev_b32_e32 v6, 16, v2
	v_and_b32_e32 v3, 0xffff0000, v3
	v_and_b32_e32 v2, 0xffff0000, v2
	v_lshlrev_b32_e32 v5, 16, v1
	v_lshlrev_b32_e32 v4, 16, v0
	v_pk_fma_f32 v[2:3], v[44:45], v[14:15], v[2:3] op_sel_hi:[0,1,1]
	v_pk_fma_f32 v[4:5], v[44:45], v[8:9], v[4:5] op_sel_hi:[0,1,1]
	v_and_b32_e32 v1, 0xffff0000, v1
	v_and_b32_e32 v0, 0xffff0000, v0
	v_bfe_u32 v8, v3, 16, 1
	v_pk_fma_f32 v[0:1], v[44:45], v[10:11], v[0:1] op_sel_hi:[0,1,1]
	v_bfe_u32 v9, v2, 16, 1
	v_add3_u32 v3, v3, v8, s13
	v_bfe_u32 v8, v4, 16, 1
	v_bfe_u32 v11, v0, 16, 1
	v_add3_u32 v2, v2, v9, s13
	v_bfe_u32 v9, v5, 16, 1
	v_add3_u32 v4, v4, v8, s13
	v_bfe_u32 v10, v1, 16, 1
	v_add3_u32 v0, v0, v11, s13
	v_add3_u32 v5, v5, v9, s13
	v_lshrrev_b32_e32 v4, 16, v4
	v_add3_u32 v1, v1, v10, s13
	v_lshrrev_b32_e32 v5, 16, v5
	v_and_or_b32 v0, v0, s14, v4
	v_lshlrev_b32_e32 v4, 2, v77
	v_and_or_b32 v1, v1, s14, v5
	v_or_b32_e32 v5, 60, v4
	v_pk_fma_f32 v[6:7], v[44:45], v[12:13], v[6:7] op_sel_hi:[0,1,1]
	v_cndmask_b32_e32 v4, v4, v5, vcc
	v_bfe_u32 v10, v6, 16, 1
	v_bfe_u32 v11, v7, 16, 1
	v_or_b32_e32 v4, v4, v76
	v_add3_u32 v7, v7, v11, s13
	v_add3_u32 v6, v6, v10, s13
	v_ashrrev_i32_e32 v5, 31, v4
	v_lshrrev_b32_e32 v6, 16, v6
	v_lshrrev_b32_e32 v7, 16, v7
	v_lshlrev_b64 v[4:5], 16, v[4:5]
	v_cmp_lt_i32_e32 vcc, s15, v70
	v_and_or_b32 v3, v3, s14, v7
	v_and_or_b32 v2, v2, s14, v6
	v_lshl_add_u64 v[4:5], v[46:47], 0, v[4:5]
	s_or_b64 s[10:11], vcc, s[10:11]
	global_store_dwordx4 v[4:5], v[0:3], off
	s_andn2_b64 exec, exec, s[10:11]
	s_cbranch_execnz .LBB0_636
